# REC_IN: dual K-loop (swapped operands for q/g), LDS-staged whole-row epilogues for q,g,i regions
# speedup vs baseline: 1.0658x; 1.0017x over previous
; DI int obid() { int b = blockIdx.x; asm volatile("" : "+s"(b)); return b; }
; DI int ogrid() { int g = gridDim.x; asm volatile("" : "+s"(g)); return g; }
; #define STAGE(bufoff, GB) do { const char* g_ = (GB); \
;         _Pragma("unroll") for (int i_ = 0; i_ < 2; ++i_) __builtin_amdgcn_global_load_lds((const unsigned*)(g_ + voff[i_]), (LAS3 unsigned*)(L + (bufoff) + stoff + i_ * 8192), 16, 0, 0); } while (0)
; #define WAIT_V(n) asm volatile("s_waitcnt vmcnt(" #n ")" ::: "memory")
; #define BAR __builtin_amdgcn_s_barrier()
; #define VOFF_INIT() do { _Pragma("unroll") for (int i = 0; i < 2; ++i) { int R, C; stage_rc((wid * 64 + olane()) * 16 + i * 8192, R, C); voff[i] = (unsigned)(R * K + C) * 2u; } } while (0)
; template <int EPI>
; DI void gemm_phase(const bf16_t* __restrict__ A, const bf16_t* __restrict__ Bt, const int K, const int N, const Params& p, const int layer_j, char* lds) {
;     ...
;     const size_t kstep = 128, hstep = (size_t)HALF * K * 2, tstep = 2 * hstep;
;     const char* cA = (const char*)A + (size_t)pm * tstep; const char* cB = (const char*)Bt + (size_t)pn * tstep;
;     f32x4 acc[2][2][4][2];
; #pragma unroll
;     for (int a = 0; a < 2; ++a)
; #pragma unroll
;         for (int b = 0; b < 2; ++b)
; #pragma unroll
;             for (int m = 0; m < 4; ++m)
; #pragma unroll
;                 for (int n = 0; n < 2; ++n) acc[a][b][m][n] = (f32x4){0.f, 0.f, 0.f, 0.f};
;     bf16x8 At[4][2], B0[2][2], B1[2][2];
;     {
;         unsigned voff[2]; VOFF_INIT();
;         asm volatile("s_waitcnt vmcnt(0) lgkmcnt(0)" ::: "memory");
;         __syncthreads();
;         STAGE(SB(0, 0), cB); STAGE(SB(0, 1), cB + hstep); STAGE(SA(0, 0), cA); STAGE(SA(0, 1), cA + hstep);
;         if (wr == 1) BAR;
;         WAIT_V(2); BAR;
;         STAGE(SB(1, 0), cB + kstep); STAGE(SA(1, 0), cA + kstep); STAGE(SB(1, 1), cB + hstep + kstep);
;         WAIT_V(6); BAR;
;     }
;     for (int ui = 0;; ++ui) {
;         const int Lnext = (ui + 1) * ogrid() + obid();
;         const bool has_next = Lnext < nwg;
;         int pm2 = pm, pn2 = pn;
;         if (has_next) TILE_COORDS(Lnext, pm2, pn2);
;         const char* nA = (const char*)A + (size_t)pm2 * tstep; const char* nB = (const char*)Bt + (size_t)pn2 * tstep;
;         unsigned voff[2]; VOFF_INIT();
.LBB0_337:
	v_mbcnt_lo_u32_b32 v0, -1, 0
	v_mbcnt_hi_u32_b32 v0, -1, v0
	s_ashr_i32 s21, s20, 31
	v_add_u32_e32 v1, s71, v0
	v_ashrrev_i32_e32 v3, 6, v1
	v_lshlrev_b32_e32 v2, 4, v1
	v_lshrrev_b32_e32 v1, 31, v3
	v_add_u32_e32 v1, v3, v1
	v_and_b32_e32 v4, 32, v0
	v_ashrrev_i32_e32 v5, 1, v1
	v_and_b32_e32 v1, 0x3fffffe, v1
	v_lshlrev_b32_e32 v0, 9, v0
	v_sub_u32_e32 v1, v3, v1
	v_and_b32_e32 v6, 48, v2
	v_bitop3_b32 v2, v2, v4, 48 bitop3:0x6c
	v_and_b32_e32 v8, 0x7800, v0
	v_lshlrev_b32_e32 v1, 6, v1
	v_lshlrev_b32_e32 v7, 15, v5
	v_or_b32_e32 v0, v8, v2
	s_ashr_i32 s23, s22, 31
	v_add3_u32 v32, v1, v7, v0
	v_mbcnt_lo_u32_b32 v0, -1, 0
	v_mbcnt_hi_u32_b32 v0, -1, v0
	s_lshl_b64 s[24:25], s[20:21], 19
	v_add_lshl_u32 v1, v0, s71, 4
	s_lshl_b64 s[26:27], s[22:23], 19
	v_add_u32_e32 v2, 0x2000, v1
	v_ashrrev_i32_e32 v2, 10, v2
	s_add_u32 s5, s82, s24
	v_and_b32_e32 v7, 32, v0
	v_lshrrev_b32_e32 v9, 31, v2
	v_lshlrev_b32_e32 v0, 9, v0
	s_addc_u32 s9, s83, s25
	v_add_u32_e32 v9, v2, v9
	v_and_b32_e32 v11, 48, v1
	v_bitop3_b32 v1, v1, v7, 48 bitop3:0x6c
	v_and_b32_e32 v0, 0x7800, v0
	s_add_u32 s21, s36, s26
	v_ashrrev_i32_e32 v10, 1, v9
	v_and_b32_e32 v9, 0x3fffffe, v9
	v_or_b32_e32 v1, v0, v1
	s_addc_u32 s23, s37, s27
	v_sub_u32_e32 v9, v2, v9
	v_lshl_or_b32 v1, v10, 15, v1
	s_add_u32 s67, s38, s30
	s_movk_i32 s6, 0x7f80
	v_lshl_add_u32 v130, v9, 6, v1
	s_addc_u32 s86, s39, s31
	v_mul_lo_u32 v1, v10, s6
	v_bitop3_b32 v1, v11, v1, v7 bitop3:0xde
	v_lshlrev_b32_e32 v2, 6, v2
	s_add_u32 s30, s64, s28
	v_add3_u32 v0, v1, v0, v2
	v_mov_b32_e32 v1, v33
	s_addc_u32 s31, s65, s29
	v_lshl_add_u64 v[132:133], s[30:31], 0, v[0:1]
	v_mul_lo_u32 v0, v5, s6
	v_bitop3_b32 v0, v6, v0, v4 bitop3:0xde
	v_lshlrev_b32_e32 v1, 6, v3
	v_add3_u32 v0, v0, v8, v1
	v_mov_b32_e32 v1, v33
	s_add_u32 s87, s68, s28
	v_mov_b32_e32 v8, 0
	v_mov_b32_e32 v131, v33
	v_lshl_add_u64 v[134:135], s[30:31], 0, v[0:1]
	s_addc_u32 s88, s69, s29
	s_mov_b32 vcc_lo, -2
	s_mov_b64 s[28:29], 0
	v_mov_b32_e32 v9, v8
	v_mov_b32_e32 v10, v8
	v_mov_b32_e32 v11, v8
	v_mov_b32_e32 v28, v8
	v_mov_b32_e32 v29, v8
	v_mov_b32_e32 v30, v8
	v_mov_b32_e32 v31, v8
	v_mov_b32_e32 v12, v8
	v_mov_b32_e32 v13, v8
	v_mov_b32_e32 v14, v8
	v_mov_b32_e32 v15, v8
	v_mov_b32_e32 v34, v8
	v_mov_b32_e32 v35, v8
	v_mov_b32_e32 v36, v8
	v_mov_b32_e32 v37, v8
	v_mov_b32_e32 v42, v8
	v_mov_b32_e32 v43, v8
	v_mov_b32_e32 v44, v8
	v_mov_b32_e32 v45, v8
	v_mov_b32_e32 v58, v8
	v_mov_b32_e32 v59, v8
	v_mov_b32_e32 v60, v8
	v_mov_b32_e32 v61, v8
	v_mov_b32_e32 v46, v8
	v_mov_b32_e32 v47, v8
	v_mov_b32_e32 v48, v8
	v_mov_b32_e32 v49, v8
	v_mov_b32_e32 v62, v8
	v_mov_b32_e32 v63, v8
	v_mov_b32_e32 v64, v8
	v_mov_b32_e32 v65, v8
	v_mov_b32_e32 v50, v8
	v_mov_b32_e32 v51, v8
	v_mov_b32_e32 v52, v8
	v_mov_b32_e32 v53, v8
	v_mov_b32_e32 v66, v8
	v_mov_b32_e32 v67, v8
	v_mov_b32_e32 v68, v8
	v_mov_b32_e32 v69, v8
	v_mov_b32_e32 v54, v8
	v_mov_b32_e32 v55, v8
	v_mov_b32_e32 v56, v8
	v_mov_b32_e32 v57, v8
	v_mov_b32_e32 v70, v8
	v_mov_b32_e32 v71, v8
	v_mov_b32_e32 v72, v8
	v_mov_b32_e32 v73, v8
	v_mov_b32_e32 v16, v8
	v_mov_b32_e32 v17, v8
	v_mov_b32_e32 v18, v8
	v_mov_b32_e32 v19, v8
	v_mov_b32_e32 v38, v8
	v_mov_b32_e32 v39, v8
	v_mov_b32_e32 v40, v8
	v_mov_b32_e32 v41, v8
	v_mov_b32_e32 v82, v8
	v_mov_b32_e32 v83, v8
	v_mov_b32_e32 v84, v8
	v_mov_b32_e32 v85, v8
	v_mov_b32_e32 v86, v8
	v_mov_b32_e32 v87, v8
	v_mov_b32_e32 v88, v8
	v_mov_b32_e32 v89, v8
	v_mov_b32_e32 v98, v8
	v_mov_b32_e32 v99, v8
	v_mov_b32_e32 v100, v8
	v_mov_b32_e32 v101, v8
	v_mov_b32_e32 v102, v8
	v_mov_b32_e32 v103, v8
	v_mov_b32_e32 v104, v8
	v_mov_b32_e32 v105, v8
	v_mov_b32_e32 v114, v8
	v_mov_b32_e32 v115, v8
	v_mov_b32_e32 v116, v8
	v_mov_b32_e32 v117, v8
	v_mov_b32_e32 v118, v8
	v_mov_b32_e32 v119, v8
	v_mov_b32_e32 v120, v8
	v_mov_b32_e32 v121, v8
	v_mov_b32_e32 v74, v8
	v_mov_b32_e32 v75, v8
	v_mov_b32_e32 v76, v8
	v_mov_b32_e32 v77, v8
	v_mov_b32_e32 v78, v8
	v_mov_b32_e32 v79, v8
	v_mov_b32_e32 v80, v8
	v_mov_b32_e32 v81, v8
	v_mov_b32_e32 v90, v8
	v_mov_b32_e32 v91, v8
	v_mov_b32_e32 v92, v8
	v_mov_b32_e32 v93, v8
	v_mov_b32_e32 v94, v8
	v_mov_b32_e32 v95, v8
	v_mov_b32_e32 v96, v8
	v_mov_b32_e32 v97, v8
	v_mov_b32_e32 v106, v8
	v_mov_b32_e32 v107, v8
	v_mov_b32_e32 v108, v8
	v_mov_b32_e32 v109, v8
	v_mov_b32_e32 v110, v8
	v_mov_b32_e32 v111, v8
	v_mov_b32_e32 v112, v8
	v_mov_b32_e32 v113, v8
	v_mov_b32_e32 v122, v8
	v_mov_b32_e32 v123, v8
	v_mov_b32_e32 v124, v8
	v_mov_b32_e32 v125, v8
	v_mov_b32_e32 v126, v8
	v_mov_b32_e32 v127, v8
	v_mov_b32_e32 v128, v8
	v_mov_b32_e32 v129, v8
	v_mov_b32_e32 v24, v8
	v_mov_b32_e32 v25, v8
	v_mov_b32_e32 v26, v8
	v_mov_b32_e32 v27, v8
	v_mov_b32_e32 v4, v8
	v_mov_b32_e32 v5, v8
	v_mov_b32_e32 v6, v8
	v_mov_b32_e32 v7, v8
	v_mov_b32_e32 v20, v8
	v_mov_b32_e32 v21, v8
	v_mov_b32_e32 v22, v8
	v_mov_b32_e32 v23, v8
	v_mov_b32_e32 v0, v8
	v_mov_b32_e32 v1, v8
	v_mov_b32_e32 v2, v8
	v_mov_b32_e32 v3, v8
	s_lshr_b32 s16, s4, 2
	s_sub_u32 s16, s16, 1
	s_cmp_lt_u32 s16, 2
	s_cbranch_scc1 .Lrec_kloop_ns
; #define STAGE(bufoff, GB) do { const char* g_ = (GB); \
;         _Pragma("unroll") for (int i_ = 0; i_ < 2; ++i_) __builtin_amdgcn_global_load_lds((const unsigned*)(g_ + voff[i_]), (LAS3 unsigned*)(L + (bufoff) + stoff + i_ * 8192), 16, 0, 0); } while (0)
; #define LDA(dst, b, h) do { _Pragma("unroll") for (int m = 0; m < 4; ++m) _Pragma("unroll") for (int k = 0; k < 2; ++k) dst[m][k] = *(const LAS3 bf16x8*)(L + SA(b, h) + aoff + m * 2048 + k * 1024); } while (0)
; #define LDB(dst, b, h) do { _Pragma("unroll") for (int n = 0; n < 2; ++n) _Pragma("unroll") for (int k = 0; k < 2; ++k) dst[n][k] = *(const LAS3 bf16x8*)(L + SB(b, h) + boff + n * 2048 + k * 1024); } while (0)
; #define WAIT_V(n) asm volatile("s_waitcnt vmcnt(" #n ")" ::: "memory")
; #define WAIT_L(n) asm volatile("s_waitcnt lgkmcnt(" #n ")" ::: "memory")
; #define BAR __builtin_amdgcn_s_barrier()
; #define SCHED __builtin_amdgcn_sched_barrier(0)
; template <int EPI>
; DI void gemm_phase(const bf16_t* __restrict__ A, const bf16_t* __restrict__ Bt, const int K, const int N, const Params& p, const int layer_j, char* lds) {
;     ...
;         for (int t = 0; t < nt; t += 2) {
;             const bool last = (t == nt - 2);
;             const char* a1 = cA + (size_t)(t + 1) * kstep;
;             const char* a2 = last ? nA : cA + (size_t)(t + 2) * kstep; const char* b2 = last ? nB : cB + (size_t)(t + 2) * kstep;
;             const char* a3 = a2 + kstep; const char* b3 = b2 + kstep;
;             LDB(B0, 0, 0); LDB(B1, 0, 1); SCHED; LDA(At, 0, 0); STAGE(SA(1, 1), a1 + hstep);
;             WAIT_V(8); WAIT_L(0); BAR; MMA(0, 0, At, B0); MMA(0, 1, At, B1); BAR; SCHED;
;             LDA(At, 0, 1); STAGE(SB(0, 0), b2); STAGE(SB(0, 1), b2 + hstep); STAGE(SA(0, 0), a2);
;             WAIT_V(8); WAIT_L(0); BAR; MMA(1, 0, At, B0); MMA(1, 1, At, B1); BAR; SCHED;
.LBB0_338:
	v_add_u32_e32 v148, 0x10000, v186
	v_add_u32_e32 v164, 0x14000, v186
	s_add_u32 s16, s87, s28
	ds_read_b128 v[136:139], v148
	ds_read_b128 v[140:143], v148 offset:1024
	ds_read_b128 v[144:147], v148 offset:2048
	ds_read_b128 v[148:151], v148 offset:3072
	ds_read_b128 v[152:155], v164
	ds_read_b128 v[156:159], v164 offset:1024
	ds_read_b128 v[160:163], v164 offset:2048
	ds_read_b128 v[164:167], v164 offset:3072
	s_addc_u32 s17, s88, s29
	s_add_u32 s16, s16, 0x6681100
	s_addc_u32 s17, s17, 0
	s_add_u32 s30, s67, s28
	s_addc_u32 s31, s86, s29
	s_cmpk_eq_i32 s28, 0x700
	s_cselect_b32 s35, s9, s17
	s_cselect_b32 s34, s5, s16
	s_cselect_b32 s31, s23, s31
	s_cselect_b32 s30, s21, s30
	v_add_u32_e32 v192, 0xc000, v184
	v_lshl_add_u64 v[194:195], v[134:135], 0, s[28:29]
	v_readfirstlane_b32 s16, v192
	v_add_u32_e32 v192, 0xe000, v184
	s_mov_b32 m0, s16
	v_readfirstlane_b32 s16, v192
	ds_read_b128 v[168:171], v185
	ds_read_b128 v[172:175], v185 offset:1024
	ds_read_b128 v[176:179], v185 offset:2048
	ds_read_b128 v[180:183], v185 offset:3072
	ds_read_b128 v[212:215], v185 offset:4096
	ds_read_b128 v[216:219], v185 offset:5120
	ds_read_b128 v[220:223], v185 offset:6144
	ds_read_b128 v[224:227], v185 offset:7168
	global_load_lds_dwordx4 v[194:195], off
	v_lshl_add_u64 v[194:195], v[132:133], 0, s[28:29]
	s_mov_b32 m0, s16
	s_nop 0
	global_load_lds_dwordx4 v[194:195], off
	s_waitcnt vmcnt(8)
	s_waitcnt lgkmcnt(0)
	s_barrier
	s_setprio 1
	s_waitcnt lgkmcnt(0)
	v_mfma_f32_16x16x32_bf16 v[126:129], v[136:139], v[168:171], v[126:129]
	v_mfma_f32_16x16x32_bf16 v[122:125], v[144:147], v[168:171], v[122:125]
	v_mfma_f32_16x16x32_bf16 v[110:113], v[136:139], v[176:179], v[110:113]
	v_mfma_f32_16x16x32_bf16 v[106:109], v[144:147], v[176:179], v[106:109]
	v_mfma_f32_16x16x32_bf16 v[94:97], v[136:139], v[212:215], v[94:97]
	v_mfma_f32_16x16x32_bf16 v[90:93], v[144:147], v[212:215], v[90:93]
	v_mfma_f32_16x16x32_bf16 v[78:81], v[136:139], v[220:223], v[78:81]
	v_mfma_f32_16x16x32_bf16 v[74:77], v[144:147], v[220:223], v[74:77]
	v_mfma_f32_16x16x32_bf16 v[126:129], v[140:143], v[172:175], v[126:129]
	v_mfma_f32_16x16x32_bf16 v[122:125], v[148:151], v[172:175], v[122:125]
	v_mfma_f32_16x16x32_bf16 v[110:113], v[140:143], v[180:183], v[110:113]
	v_mfma_f32_16x16x32_bf16 v[106:109], v[148:151], v[180:183], v[106:109]
	v_mfma_f32_16x16x32_bf16 v[94:97], v[140:143], v[216:219], v[94:97]
	v_mfma_f32_16x16x32_bf16 v[90:93], v[148:151], v[216:219], v[90:93]
	v_mfma_f32_16x16x32_bf16 v[78:81], v[140:143], v[224:227], v[78:81]
	v_mfma_f32_16x16x32_bf16 v[74:77], v[148:151], v[224:227], v[74:77]
	s_setprio 0
	s_setprio 1
	v_mfma_f32_16x16x32_bf16 v[118:121], v[152:155], v[168:171], v[118:121]
	v_mfma_f32_16x16x32_bf16 v[114:117], v[160:163], v[168:171], v[114:117]
	v_mfma_f32_16x16x32_bf16 v[102:105], v[152:155], v[176:179], v[102:105]
	v_mfma_f32_16x16x32_bf16 v[98:101], v[160:163], v[176:179], v[98:101]
	v_mfma_f32_16x16x32_bf16 v[86:89], v[152:155], v[212:215], v[86:89]
	v_mfma_f32_16x16x32_bf16 v[82:85], v[160:163], v[212:215], v[82:85]
	v_mfma_f32_16x16x32_bf16 v[38:41], v[152:155], v[220:223], v[38:41]
	v_mfma_f32_16x16x32_bf16 v[16:19], v[160:163], v[220:223], v[16:19]
	v_mfma_f32_16x16x32_bf16 v[118:121], v[156:159], v[172:175], v[118:121]
	v_mfma_f32_16x16x32_bf16 v[114:117], v[164:167], v[172:175], v[114:117]
	v_mfma_f32_16x16x32_bf16 v[102:105], v[156:159], v[180:183], v[102:105]
	v_mfma_f32_16x16x32_bf16 v[98:101], v[164:167], v[180:183], v[98:101]
	v_mfma_f32_16x16x32_bf16 v[86:89], v[156:159], v[216:219], v[86:89]
	v_mfma_f32_16x16x32_bf16 v[82:85], v[164:167], v[216:219], v[82:85]
	v_mfma_f32_16x16x32_bf16 v[38:41], v[156:159], v[224:227], v[38:41]
	v_mfma_f32_16x16x32_bf16 v[16:19], v[164:167], v[224:227], v[16:19]
	s_setprio 0
	s_barrier
	v_readfirstlane_b32 s16, v187
	v_lshl_add_u64 v[194:195], s[30:31], 0, v[32:33]
	s_mov_b32 m0, s16
	v_readfirstlane_b32 s16, v188
	ds_read_b128 v[168:171], v185 offset:16384
	ds_read_b128 v[172:175], v185 offset:17408
	ds_read_b128 v[176:179], v185 offset:18432
	ds_read_b128 v[180:183], v185 offset:19456
	ds_read_b128 v[212:215], v185 offset:20480
	ds_read_b128 v[216:219], v185 offset:21504
	ds_read_b128 v[220:223], v185 offset:22528
	ds_read_b128 v[224:227], v185 offset:23552
	global_load_lds_dwordx4 v[194:195], off
	s_mov_b32 m0, s16
	s_add_u32 s16, s30, 0x40000
	v_lshl_add_u64 v[228:229], s[30:31], 0, v[130:131]
	s_addc_u32 s17, s31, 0
	v_readfirstlane_b32 s6, v189
	global_load_lds_dwordx4 v[228:229], off
	v_lshl_add_u64 v[230:231], s[16:17], 0, v[32:33]
	s_mov_b32 m0, s6
	v_readfirstlane_b32 s6, v190
	global_load_lds_dwordx4 v[230:231], off
	v_lshl_add_u64 v[230:231], s[16:17], 0, v[130:131]
	s_mov_b32 m0, s6
	v_readfirstlane_b32 s6, v184
	global_load_lds_dwordx4 v[230:231], off
	v_lshl_add_u64 v[230:231], s[34:35], 0, v[32:33]
	s_mov_b32 m0, s6
	v_readfirstlane_b32 s6, v191
	global_load_lds_dwordx4 v[230:231], off
	v_lshl_add_u64 v[232:233], s[34:35], 0, v[130:131]
	s_mov_b32 m0, s6
	s_nop 0
	global_load_lds_dwordx4 v[232:233], off
	s_waitcnt vmcnt(8)
	s_waitcnt lgkmcnt(0)
	s_barrier
; #define STAGE(bufoff, GB) do { const char* g_ = (GB); \
;         _Pragma("unroll") for (int i_ = 0; i_ < 2; ++i_) __builtin_amdgcn_global_load_lds((const unsigned*)(g_ + voff[i_]), (LAS3 unsigned*)(L + (bufoff) + stoff + i_ * 8192), 16, 0, 0); } while (0)
; #define LDA(dst, b, h) do { _Pragma("unroll") for (int m = 0; m < 4; ++m) _Pragma("unroll") for (int k = 0; k < 2; ++k) dst[m][k] = *(const LAS3 bf16x8*)(L + SA(b, h) + aoff + m * 2048 + k * 1024); } while (0)
; #define LDB(dst, b, h) do { _Pragma("unroll") for (int n = 0; n < 2; ++n) _Pragma("unroll") for (int k = 0; k < 2; ++k) dst[n][k] = *(const LAS3 bf16x8*)(L + SB(b, h) + boff + n * 2048 + k * 1024); } while (0)
; #define WAIT_V(n) asm volatile("s_waitcnt vmcnt(" #n ")" ::: "memory")
; #define WAIT_L(n) asm volatile("s_waitcnt lgkmcnt(" #n ")" ::: "memory")
; #define BAR __builtin_amdgcn_s_barrier()
; #define SCHED __builtin_amdgcn_sched_barrier(0)
; template <int EPI>
; DI void gemm_phase(const bf16_t* __restrict__ A, const bf16_t* __restrict__ Bt, const int K, const int N, const Params& p, const int layer_j, char* lds) {
;     ...
;             WAIT_V(8); WAIT_L(0); BAR; MMA(1, 0, At, B0); MMA(1, 1, At, B1); BAR; SCHED;
;             LDB(B0, 1, 0); LDB(B1, 1, 1); SCHED; LDA(At, 1, 0); STAGE(SA(0, 1), a2 + hstep);
;             WAIT_V(8); WAIT_L(0); BAR; MMA(0, 0, At, B0); MMA(0, 1, At, B1); BAR; SCHED;
;             LDA(At, 1, 1); STAGE(SB(1, 0), b3); STAGE(SB(1, 1), b3 + hstep); STAGE(SA(1, 0), a3);
;             WAIT_V(8); WAIT_L(0); BAR; MMA(1, 0, At, B0); MMA(1, 1, At, B1); BAR; SCHED;
	s_setprio 1
	s_waitcnt lgkmcnt(0)
	v_mfma_f32_16x16x32_bf16 v[70:73], v[136:139], v[168:171], v[70:73]
	v_mfma_f32_16x16x32_bf16 v[54:57], v[144:147], v[168:171], v[54:57]
	v_mfma_f32_16x16x32_bf16 v[66:69], v[136:139], v[176:179], v[66:69]
	v_mfma_f32_16x16x32_bf16 v[50:53], v[144:147], v[176:179], v[50:53]
	v_mfma_f32_16x16x32_bf16 v[62:65], v[136:139], v[212:215], v[62:65]
	v_mfma_f32_16x16x32_bf16 v[46:49], v[144:147], v[212:215], v[46:49]
	v_mfma_f32_16x16x32_bf16 v[58:61], v[136:139], v[220:223], v[58:61]
	v_mfma_f32_16x16x32_bf16 v[42:45], v[144:147], v[220:223], v[42:45]
	v_mfma_f32_16x16x32_bf16 v[70:73], v[140:143], v[172:175], v[70:73]
	v_mfma_f32_16x16x32_bf16 v[54:57], v[148:151], v[172:175], v[54:57]
	v_mfma_f32_16x16x32_bf16 v[66:69], v[140:143], v[180:183], v[66:69]
	v_mfma_f32_16x16x32_bf16 v[50:53], v[148:151], v[180:183], v[50:53]
	v_mfma_f32_16x16x32_bf16 v[62:65], v[140:143], v[216:219], v[62:65]
	v_mfma_f32_16x16x32_bf16 v[46:49], v[148:151], v[216:219], v[46:49]
	v_mfma_f32_16x16x32_bf16 v[58:61], v[140:143], v[224:227], v[58:61]
	v_mfma_f32_16x16x32_bf16 v[42:45], v[148:151], v[224:227], v[42:45]
	s_setprio 0
	s_setprio 1
	v_mfma_f32_16x16x32_bf16 v[34:37], v[152:155], v[168:171], v[34:37]
	v_mfma_f32_16x16x32_bf16 v[12:15], v[160:163], v[168:171], v[12:15]
	v_mfma_f32_16x16x32_bf16 v[28:31], v[152:155], v[176:179], v[28:31]
	v_mfma_f32_16x16x32_bf16 v[8:11], v[160:163], v[176:179], v[8:11]
	v_mfma_f32_16x16x32_bf16 v[24:27], v[152:155], v[212:215], v[24:27]
	v_mfma_f32_16x16x32_bf16 v[4:7], v[160:163], v[212:215], v[4:7]
	v_mfma_f32_16x16x32_bf16 v[20:23], v[152:155], v[220:223], v[20:23]
	v_mfma_f32_16x16x32_bf16 v[0:3], v[160:163], v[220:223], v[0:3]
	v_mfma_f32_16x16x32_bf16 v[34:37], v[156:159], v[172:175], v[34:37]
	v_mfma_f32_16x16x32_bf16 v[12:15], v[164:167], v[172:175], v[12:15]
	v_mfma_f32_16x16x32_bf16 v[28:31], v[156:159], v[180:183], v[28:31]
	v_mfma_f32_16x16x32_bf16 v[8:11], v[164:167], v[180:183], v[8:11]
	v_mfma_f32_16x16x32_bf16 v[24:27], v[156:159], v[216:219], v[24:27]
	v_mfma_f32_16x16x32_bf16 v[4:7], v[164:167], v[216:219], v[4:7]
	v_mfma_f32_16x16x32_bf16 v[20:23], v[156:159], v[224:227], v[20:23]
	v_mfma_f32_16x16x32_bf16 v[0:3], v[164:167], v[224:227], v[0:3]
	s_setprio 0
	s_barrier
	v_add_u32_e32 v148, 0x18000, v186
	v_add_u32_e32 v164, 0x1c000, v186
	ds_read_b128 v[136:139], v148
	ds_read_b128 v[140:143], v148 offset:1024
	ds_read_b128 v[144:147], v148 offset:2048
	ds_read_b128 v[148:151], v148 offset:3072
	ds_read_b128 v[152:155], v164
	ds_read_b128 v[156:159], v164 offset:1024
	ds_read_b128 v[160:163], v164 offset:2048
	ds_read_b128 v[164:167], v164 offset:3072
	s_add_u32 s16, s34, 0x40000
	s_addc_u32 s17, s35, 0
	v_readfirstlane_b32 s6, v204
	v_lshl_add_u64 v[234:235], s[16:17], 0, v[32:33]
	s_mov_b32 m0, s6
	v_readfirstlane_b32 s6, v205
	ds_read_b128 v[168:171], v185 offset:32768
	ds_read_b128 v[172:175], v185 offset:33792
	ds_read_b128 v[176:179], v185 offset:34816
	ds_read_b128 v[180:183], v185 offset:35840
	ds_read_b128 v[212:215], v185 offset:36864
	ds_read_b128 v[216:219], v185 offset:37888
	ds_read_b128 v[220:223], v185 offset:38912
	ds_read_b128 v[224:227], v185 offset:39936
	global_load_lds_dwordx4 v[234:235], off
	v_lshl_add_u64 v[234:235], s[16:17], 0, v[130:131]
	s_mov_b32 m0, s6
	s_nop 0
	global_load_lds_dwordx4 v[234:235], off
	s_waitcnt vmcnt(8)
	s_waitcnt lgkmcnt(0)
	s_barrier
	s_setprio 1
	s_waitcnt lgkmcnt(0)
	v_mfma_f32_16x16x32_bf16 v[126:129], v[136:139], v[168:171], v[126:129]
	v_mfma_f32_16x16x32_bf16 v[122:125], v[144:147], v[168:171], v[122:125]
	v_mfma_f32_16x16x32_bf16 v[110:113], v[136:139], v[176:179], v[110:113]
	v_mfma_f32_16x16x32_bf16 v[106:109], v[144:147], v[176:179], v[106:109]
	v_mfma_f32_16x16x32_bf16 v[94:97], v[136:139], v[212:215], v[94:97]
	v_mfma_f32_16x16x32_bf16 v[90:93], v[144:147], v[212:215], v[90:93]
	v_mfma_f32_16x16x32_bf16 v[78:81], v[136:139], v[220:223], v[78:81]
	v_mfma_f32_16x16x32_bf16 v[74:77], v[144:147], v[220:223], v[74:77]
	v_mfma_f32_16x16x32_bf16 v[126:129], v[140:143], v[172:175], v[126:129]
	v_mfma_f32_16x16x32_bf16 v[122:125], v[148:151], v[172:175], v[122:125]
	v_mfma_f32_16x16x32_bf16 v[110:113], v[140:143], v[180:183], v[110:113]
	v_mfma_f32_16x16x32_bf16 v[106:109], v[148:151], v[180:183], v[106:109]
	v_mfma_f32_16x16x32_bf16 v[94:97], v[140:143], v[216:219], v[94:97]
	v_mfma_f32_16x16x32_bf16 v[90:93], v[148:151], v[216:219], v[90:93]
	v_mfma_f32_16x16x32_bf16 v[78:81], v[140:143], v[224:227], v[78:81]
	v_mfma_f32_16x16x32_bf16 v[74:77], v[148:151], v[224:227], v[74:77]
	s_setprio 0
	s_setprio 1
	v_mfma_f32_16x16x32_bf16 v[118:121], v[152:155], v[168:171], v[118:121]
	v_mfma_f32_16x16x32_bf16 v[114:117], v[160:163], v[168:171], v[114:117]
	v_mfma_f32_16x16x32_bf16 v[102:105], v[152:155], v[176:179], v[102:105]
	v_mfma_f32_16x16x32_bf16 v[98:101], v[160:163], v[176:179], v[98:101]
	v_mfma_f32_16x16x32_bf16 v[86:89], v[152:155], v[212:215], v[86:89]
	v_mfma_f32_16x16x32_bf16 v[82:85], v[160:163], v[212:215], v[82:85]
	v_mfma_f32_16x16x32_bf16 v[38:41], v[152:155], v[220:223], v[38:41]
	v_mfma_f32_16x16x32_bf16 v[16:19], v[160:163], v[220:223], v[16:19]
	v_mfma_f32_16x16x32_bf16 v[118:121], v[156:159], v[172:175], v[118:121]
	v_mfma_f32_16x16x32_bf16 v[114:117], v[164:167], v[172:175], v[114:117]
	v_mfma_f32_16x16x32_bf16 v[102:105], v[156:159], v[180:183], v[102:105]
	v_mfma_f32_16x16x32_bf16 v[98:101], v[164:167], v[180:183], v[98:101]
	v_mfma_f32_16x16x32_bf16 v[86:89], v[156:159], v[216:219], v[86:89]
	v_mfma_f32_16x16x32_bf16 v[82:85], v[164:167], v[216:219], v[82:85]
	v_mfma_f32_16x16x32_bf16 v[38:41], v[156:159], v[224:227], v[38:41]
	v_mfma_f32_16x16x32_bf16 v[16:19], v[164:167], v[224:227], v[16:19]
	s_setprio 0
	s_barrier
; #define STAGE(bufoff, GB) do { const char* g_ = (GB); \
;         _Pragma("unroll") for (int i_ = 0; i_ < 2; ++i_) __builtin_amdgcn_global_load_lds((const unsigned*)(g_ + voff[i_]), (LAS3 unsigned*)(L + (bufoff) + stoff + i_ * 8192), 16, 0, 0); } while (0)
; #define LDA(dst, b, h) do { _Pragma("unroll") for (int m = 0; m < 4; ++m) _Pragma("unroll") for (int k = 0; k < 2; ++k) dst[m][k] = *(const LAS3 bf16x8*)(L + SA(b, h) + aoff + m * 2048 + k * 1024); } while (0)
; #define WAIT_V(n) asm volatile("s_waitcnt vmcnt(" #n ")" ::: "memory")
; #define WAIT_L(n) asm volatile("s_waitcnt lgkmcnt(" #n ")" ::: "memory")
; #define BAR __builtin_amdgcn_s_barrier()
; #define SCHED __builtin_amdgcn_sched_barrier(0)
; template <int EPI>
; DI void gemm_phase(const bf16_t* __restrict__ A, const bf16_t* __restrict__ Bt, const int K, const int N, const Params& p, const int layer_j, char* lds) {
;     ...
;             LDA(At, 1, 1); STAGE(SB(1, 0), b3); STAGE(SB(1, 1), b3 + hstep); STAGE(SA(1, 0), a3);
;             WAIT_V(8); WAIT_L(0); BAR; MMA(1, 0, At, B0); MMA(1, 1, At, B1); BAR; SCHED;
;         }
	v_readfirstlane_b32 s6, v206
	v_lshl_add_u64 v[194:195], v[194:195], 0, s[94:95]
	s_mov_b32 m0, s6
	v_readfirstlane_b32 s6, v207
	s_add_u32 s16, s30, 0x40080
	ds_read_b128 v[168:171], v185 offset:49152
	ds_read_b128 v[172:175], v185 offset:50176
	ds_read_b128 v[176:179], v185 offset:51200
	ds_read_b128 v[180:183], v185 offset:52224
	ds_read_b128 v[212:215], v185 offset:53248
	ds_read_b128 v[216:219], v185 offset:54272
	ds_read_b128 v[220:223], v185 offset:55296
	ds_read_b128 v[224:227], v185 offset:56320
	global_load_lds_dwordx4 v[194:195], off
	v_lshl_add_u64 v[194:195], v[228:229], 0, s[94:95]
	s_mov_b32 m0, s6
	s_addc_u32 s17, s31, 0
	v_readfirstlane_b32 s6, v210
	global_load_lds_dwordx4 v[194:195], off
	v_lshl_add_u64 v[194:195], s[16:17], 0, v[32:33]
	s_mov_b32 m0, s6
	v_readfirstlane_b32 s6, v211
	global_load_lds_dwordx4 v[194:195], off
	v_lshl_add_u64 v[194:195], s[16:17], 0, v[130:131]
	s_mov_b32 m0, s6
	v_readfirstlane_b32 s6, v208
	global_load_lds_dwordx4 v[194:195], off
	v_lshl_add_u64 v[194:195], v[230:231], 0, s[94:95]
	s_mov_b32 m0, s6
	v_readfirstlane_b32 s6, v209
	global_load_lds_dwordx4 v[194:195], off
	v_lshl_add_u64 v[194:195], v[232:233], 0, s[94:95]
	s_mov_b32 m0, s6
	s_nop 0
	global_load_lds_dwordx4 v[194:195], off
	s_waitcnt vmcnt(8)
	s_waitcnt lgkmcnt(0)
	s_barrier
	s_setprio 1
	s_waitcnt lgkmcnt(0)
	v_mfma_f32_16x16x32_bf16 v[70:73], v[136:139], v[168:171], v[70:73]
	v_mfma_f32_16x16x32_bf16 v[54:57], v[144:147], v[168:171], v[54:57]
	v_mfma_f32_16x16x32_bf16 v[66:69], v[136:139], v[176:179], v[66:69]
	v_mfma_f32_16x16x32_bf16 v[50:53], v[144:147], v[176:179], v[50:53]
	v_mfma_f32_16x16x32_bf16 v[62:65], v[136:139], v[212:215], v[62:65]
	v_mfma_f32_16x16x32_bf16 v[46:49], v[144:147], v[212:215], v[46:49]
	v_mfma_f32_16x16x32_bf16 v[58:61], v[136:139], v[220:223], v[58:61]
	v_mfma_f32_16x16x32_bf16 v[42:45], v[144:147], v[220:223], v[42:45]
	v_mfma_f32_16x16x32_bf16 v[70:73], v[140:143], v[172:175], v[70:73]
	v_mfma_f32_16x16x32_bf16 v[54:57], v[148:151], v[172:175], v[54:57]
	v_mfma_f32_16x16x32_bf16 v[66:69], v[140:143], v[180:183], v[66:69]
	v_mfma_f32_16x16x32_bf16 v[50:53], v[148:151], v[180:183], v[50:53]
	v_mfma_f32_16x16x32_bf16 v[62:65], v[140:143], v[216:219], v[62:65]
	v_mfma_f32_16x16x32_bf16 v[46:49], v[148:151], v[216:219], v[46:49]
	v_mfma_f32_16x16x32_bf16 v[58:61], v[140:143], v[224:227], v[58:61]
	v_mfma_f32_16x16x32_bf16 v[42:45], v[148:151], v[224:227], v[42:45]
	s_setprio 0
	s_setprio 1
	v_mfma_f32_16x16x32_bf16 v[34:37], v[152:155], v[168:171], v[34:37]
	v_mfma_f32_16x16x32_bf16 v[12:15], v[160:163], v[168:171], v[12:15]
	v_mfma_f32_16x16x32_bf16 v[28:31], v[152:155], v[176:179], v[28:31]
	v_mfma_f32_16x16x32_bf16 v[8:11], v[160:163], v[176:179], v[8:11]
	v_mfma_f32_16x16x32_bf16 v[24:27], v[152:155], v[212:215], v[24:27]
	v_mfma_f32_16x16x32_bf16 v[4:7], v[160:163], v[212:215], v[4:7]
	v_mfma_f32_16x16x32_bf16 v[20:23], v[152:155], v[220:223], v[20:23]
	v_mfma_f32_16x16x32_bf16 v[0:3], v[160:163], v[220:223], v[0:3]
	v_mfma_f32_16x16x32_bf16 v[34:37], v[156:159], v[172:175], v[34:37]
	v_mfma_f32_16x16x32_bf16 v[12:15], v[164:167], v[172:175], v[12:15]
	v_mfma_f32_16x16x32_bf16 v[28:31], v[156:159], v[180:183], v[28:31]
	v_mfma_f32_16x16x32_bf16 v[8:11], v[164:167], v[180:183], v[8:11]
	v_mfma_f32_16x16x32_bf16 v[24:27], v[156:159], v[216:219], v[24:27]
	v_mfma_f32_16x16x32_bf16 v[4:7], v[164:167], v[216:219], v[4:7]
	v_mfma_f32_16x16x32_bf16 v[20:23], v[156:159], v[224:227], v[20:23]
	v_mfma_f32_16x16x32_bf16 v[0:3], v[164:167], v[224:227], v[0:3]
	s_setprio 0
	s_barrier
	s_add_i32 vcc_lo, vcc_lo, 2
	s_add_u32 s28, s28, 0x100
	s_addc_u32 s29, s29, 0
	s_cmp_gt_u32 vcc_lo, 13
	s_cbranch_scc0 .LBB0_338
	s_branch .Lrec_kloop_done

; DI int olane() { int l; asm volatile("v_mbcnt_lo_u32_b32 %0, -1, 0\n\tv_mbcnt_hi_u32_b32 %0, -1, %0" : "=v"(l)); return l; }
; DI unsigned pk_bf16(float a, float b) { f32x2_t v = {a, b}; bf16x2_t r = __builtin_convertvector(v, bf16x2_t); return __builtin_bit_cast(unsigned, r); }
; #define BAR __builtin_amdgcn_s_barrier()
; template <int EPI>
; DI void gemm_phase(const bf16_t* __restrict__ A, const bf16_t* __restrict__ Bt, const int K, const int N, const Params& p, const int layer_j, char* lds) {
;     ...
;         if (wr == 0) BAR;
;         const int le = olane(), fr = le & 15, fq = le >> 4;
;         const int row0 = pm * 256 + wr * 64 + fq * 4;
;     ...
;         } else if (EPI == EPI_REC_IN) {
;             bf16_t* PROJ = (bf16_t*)(ws + OFF_P);
;             bf16_t* IT = PROJ + (size_t)M_TOK * ATT_IN;
;             const int region = col0 >> 10;
;             if (region == 2) {
;                 const int vc0 = col0 - 2048;
;                 const int b = row0 >> 11, t0 = row0 & 2047;
;                 bf16_t* dst = IT + ((size_t)(b * 1024 + vc0 + fr)) * SEQ + t0;
; #pragma unroll
;                 for (int bj = 0; bj < 2; ++bj)
; #pragma unroll
;                     for (int n = 0; n < 2; ++n)
; #pragma unroll
;                         for (int ai = 0; ai < 2; ++ai)
; #pragma unroll
;                             for (int m = 0; m < 4; ++m) { u32x2 o; o[0] = pk_bf16(acc[ai][bj][m][n][0], acc[ai][bj][m][n][1]); o[1] = pk_bf16(acc[ai][bj][m][n][2], acc[ai][bj][m][n][3]);
;                                 *(u32x2*)(dst + (size_t)(bj * 32 + n * 16) * SEQ + ai * 128 + m * 16) = o; }
.Lrec_kloop_done:
	v_readlane_b32 s6, v254, 12
	v_readlane_b32 s7, v254, 13
	s_and_b64 vcc, exec, s[6:7]
	s_cbranch_vccz .LBB0_341
	s_barrier
.LBB0_341:
	v_mbcnt_lo_u32_b32 v32, -1, 0
	v_mbcnt_hi_u32_b32 v32, -1, v32
	s_lshl_b32 s5, s8, 8
	v_and_b32_e32 v130, 15, v32
	v_readlane_b32 s6, v254, 7
	v_ashrrev_i32_e32 v32, 2, v32
	s_add_i32 s5, s5, s6
	v_and_b32_e32 v32, -4, v32
	v_add_u32_e32 v132, s5, v32
	s_lshl_b32 s5, s4, 8
	v_readlane_b32 s6, v254, 14
	s_or_b32 s28, s5, s6
	s_ashr_i32 s5, s4, 2
	s_mov_b32 s86, 0x3a800000
	s_movk_i32 s67, 0x1000
	s_movk_i32 s87, 0x3fff
	s_cmp_eq_u32 s5, 0
	s_cbranch_scc1 .Lrec_epi_silu
	s_cmp_eq_u32 s5, 3
	s_cbranch_scc1 .Lrec_epi_silu
	s_cmp_eq_u32 s5, 2
	s_cbranch_scc1 .Lrec_epi_tr
	s_mov_b64 s[34:35], -1
	s_mov_b64 s[8:9], 0
	s_cmp_lt_i32 s5, 2
	s_mov_b64 s[30:31], 0
	s_cbranch_scc1 .LBB0_345
	s_cmp_eq_u32 s5, 2
	s_mov_b64 s[30:31], -1
	s_cbranch_scc0 .LBB0_344
	s_add_i32 s6, s28, 0xfffff800
	v_ashrrev_i32_e32 v131, 1, v132
	v_and_b32_e32 v131, 0xfffffc00, v131
	v_or_b32_e32 v133, s6, v130
	v_add_u32_e32 v134, v133, v131
	v_ashrrev_i32_e32 v135, 31, v134
	v_readlane_b32 s6, v255, 8
	v_and_b32_e32 v32, 0x7fc, v132
	v_lshlrev_b64 v[134:135], 12, v[134:135]
	v_readlane_b32 s7, v255, 9
	v_lshlrev_b32_e32 v32, 1, v32
	v_cvt_pk_bf16_f32 v136, v126, v127
	v_lshl_add_u64 v[134:135], s[6:7], 0, v[134:135]
	v_lshl_add_u64 v[134:135], v[134:135], 0, v[32:33]
	v_cvt_pk_bf16_f32 v137, v128, v129
	s_waitcnt vmcnt(0)
	flat_store_dwordx2 v[134:135], v[136:137]
	v_cvt_pk_bf16_f32 v136, v110, v111
	v_cvt_pk_bf16_f32 v137, v112, v113
	flat_store_dwordx2 v[134:135], v[136:137] offset:32
	v_cvt_pk_bf16_f32 v136, v94, v95
	v_cvt_pk_bf16_f32 v137, v96, v97
	flat_store_dwordx2 v[134:135], v[136:137] offset:64
	v_cvt_pk_bf16_f32 v136, v78, v79
	v_cvt_pk_bf16_f32 v137, v80, v81
	flat_store_dwordx2 v[134:135], v[136:137] offset:96
	v_cvt_pk_bf16_f32 v136, v70, v71
	v_cvt_pk_bf16_f32 v137, v72, v73
	flat_store_dwordx2 v[134:135], v[136:137] offset:256
	v_cvt_pk_bf16_f32 v136, v66, v67
	v_cvt_pk_bf16_f32 v137, v68, v69
	flat_store_dwordx2 v[134:135], v[136:137] offset:288
	v_cvt_pk_bf16_f32 v136, v62, v63
	v_cvt_pk_bf16_f32 v137, v64, v65
	s_mov_b32 s6, 0x10000
	flat_store_dwordx2 v[134:135], v[136:137] offset:320
	v_cvt_pk_bf16_f32 v136, v58, v59
	v_cvt_pk_bf16_f32 v137, v60, v61
	v_add_co_u32_e32 v138, vcc, s6, v134
	flat_store_dwordx2 v[134:135], v[136:137] offset:352
	v_cvt_pk_bf16_f32 v136, v122, v123
	v_cvt_pk_bf16_f32 v137, v124, v125
	v_addc_co_u32_e32 v139, vcc, 0, v135, vcc
	flat_store_dwordx2 v[138:139], v[136:137]
	v_cvt_pk_bf16_f32 v136, v106, v107
	v_cvt_pk_bf16_f32 v137, v108, v109
	flat_store_dwordx2 v[138:139], v[136:137] offset:32
	v_cvt_pk_bf16_f32 v136, v90, v91
	v_cvt_pk_bf16_f32 v137, v92, v93
	flat_store_dwordx2 v[138:139], v[136:137] offset:64
	v_cvt_pk_bf16_f32 v136, v74, v75
	v_cvt_pk_bf16_f32 v137, v76, v77
	flat_store_dwordx2 v[138:139], v[136:137] offset:96
	v_cvt_pk_bf16_f32 v136, v54, v55
	v_cvt_pk_bf16_f32 v137, v56, v57
	flat_store_dwordx2 v[138:139], v[136:137] offset:256
	v_cvt_pk_bf16_f32 v136, v50, v51
	v_cvt_pk_bf16_f32 v137, v52, v53
	flat_store_dwordx2 v[138:139], v[136:137] offset:288
	v_cvt_pk_bf16_f32 v136, v46, v47
	v_cvt_pk_bf16_f32 v137, v48, v49
	flat_store_dwordx2 v[138:139], v[136:137] offset:320
	v_cvt_pk_bf16_f32 v136, v42, v43
	v_cvt_pk_bf16_f32 v137, v44, v45
	s_mov_b32 s6, 0x20000
	flat_store_dwordx2 v[138:139], v[136:137] offset:352
	v_add_co_u32_e32 v138, vcc, s6, v134
	v_cvt_pk_bf16_f32 v136, v118, v119
	v_cvt_pk_bf16_f32 v137, v120, v121
	v_addc_co_u32_e32 v139, vcc, 0, v135, vcc
	flat_store_dwordx2 v[138:139], v[136:137]
	v_cvt_pk_bf16_f32 v136, v102, v103
	v_cvt_pk_bf16_f32 v137, v104, v105
	flat_store_dwordx2 v[138:139], v[136:137] offset:32
	v_cvt_pk_bf16_f32 v136, v86, v87
	v_cvt_pk_bf16_f32 v137, v88, v89
	flat_store_dwordx2 v[138:139], v[136:137] offset:64
	v_cvt_pk_bf16_f32 v136, v38, v39
	v_cvt_pk_bf16_f32 v137, v40, v41
	flat_store_dwordx2 v[138:139], v[136:137] offset:96
	v_cvt_pk_bf16_f32 v136, v34, v35
	v_cvt_pk_bf16_f32 v137, v36, v37
	flat_store_dwordx2 v[138:139], v[136:137] offset:256
	v_cvt_pk_bf16_f32 v136, v28, v29
	v_cvt_pk_bf16_f32 v137, v30, v31
	flat_store_dwordx2 v[138:139], v[136:137] offset:288
	v_cvt_pk_bf16_f32 v136, v24, v25
	v_cvt_pk_bf16_f32 v137, v26, v27
	flat_store_dwordx2 v[138:139], v[136:137] offset:320
	v_cvt_pk_bf16_f32 v136, v20, v21
	v_cvt_pk_bf16_f32 v137, v22, v23
	v_add_co_u32_e32 v134, vcc, s3, v134
	flat_store_dwordx2 v[138:139], v[136:137] offset:352
	v_cvt_pk_bf16_f32 v136, v114, v115
	v_cvt_pk_bf16_f32 v137, v116, v117
	v_addc_co_u32_e32 v135, vcc, 0, v135, vcc
	flat_store_dwordx2 v[134:135], v[136:137]
	v_cvt_pk_bf16_f32 v136, v98, v99
	v_cvt_pk_bf16_f32 v137, v100, v101
	flat_store_dwordx2 v[134:135], v[136:137] offset:32
	v_cvt_pk_bf16_f32 v136, v82, v83
	v_cvt_pk_bf16_f32 v137, v84, v85
	flat_store_dwordx2 v[134:135], v[136:137] offset:64
	v_cvt_pk_bf16_f32 v136, v16, v17
	v_cvt_pk_bf16_f32 v137, v18, v19
	flat_store_dwordx2 v[134:135], v[136:137] offset:96
	v_cvt_pk_bf16_f32 v136, v12, v13
	v_cvt_pk_bf16_f32 v137, v14, v15
	flat_store_dwordx2 v[134:135], v[136:137] offset:256
	v_cvt_pk_bf16_f32 v136, v8, v9
	v_cvt_pk_bf16_f32 v137, v10, v11
	flat_store_dwordx2 v[134:135], v[136:137] offset:288
	v_cvt_pk_bf16_f32 v136, v4, v5
	v_cvt_pk_bf16_f32 v137, v6, v7
	flat_store_dwordx2 v[134:135], v[136:137] offset:320
	v_cvt_pk_bf16_f32 v136, v0, v1
	v_cvt_pk_bf16_f32 v137, v2, v3
	flat_store_dwordx2 v[134:135], v[136:137] offset:352
	s_mov_b64 s[30:31], 0

; DI bf16_t f2bf(float a) { return (bf16_t)(pk_bf16(a, 0.f) & 0xffffu); }
; DI float silu_f(float x) { return x * __builtin_amdgcn_rcpf(1.f + __expf(-x)); }
; template <int EPI>
; DI void gemm_phase(const bf16_t* __restrict__ A, const bf16_t* __restrict__ Bt, const int K, const int N, const Params& p, const int layer_j, char* lds) {
;     ...
;             } else {
;                 const int dc0 = (region == 0) ? col0 : (col0 - 3072 + 2048);
;                 const float sc = (region == 0) ? 0.08838834764831845f : 1.0f;
;                 bf16_t* dst = PROJ + (size_t)row0 * ATT_IN + dc0 + fr;
; #pragma unroll
;                 for (int ai = 0; ai < 2; ++ai)
; #pragma unroll
;                     for (int m = 0; m < 4; ++m)
; #pragma unroll
;                         for (int j = 0; j < 4; ++j)
; #pragma unroll
;                             for (int bj = 0; bj < 2; ++bj)
; #pragma unroll
;                                 for (int n = 0; n < 2; ++n) dst[(size_t)(ai * 128 + m * 16 + j) * ATT_IN + bj * 32 + n * 16] = f2bf(silu_f(acc[ai][bj][m][n][j]) * sc);
;             }
.Lrec_epi_silu:
	v_mbcnt_lo_u32_b32 v212, -1, 0
	v_mbcnt_hi_u32_b32 v212, -1, v212
	s_mul_i32 s16, s71, 34
	s_add_i32 s16, s16, 0x20100
	v_and_b32_e32 v213, 15, v212
	v_lshrrev_b32_e32 v214, 4, v212
	v_mul_u32_u24_e32 v213, 136, v213
	v_lshl_add_u32 v213, v214, 3, v213
	v_add_u32_e32 v213, s16, v213
	v_lshrrev_b32_e32 v215, 3, v212
	v_and_b32_e32 v216, 7, v212
	v_mul_u32_u24_e32 v214, 136, v215
	v_lshl_add_u32 v214, v216, 4, v214
	v_add_u32_e32 v214, s16, v214
	v_readlane_b32 s16, v254, 7
	v_readlane_b32 s17, v254, 14
	v_lshlrev_b32_e32 v216, 4, v216
	v_add_u32_e32 v215, s16, v215
	s_lshl_b32 s17, s17, 1
	s_mov_b32 s16, 6144
	v_mad_u32_u24 v215, v215, s16, v216
	v_add_u32_e32 v215, s17, v215
	v_add_u32_e32 v216, 0xc000, v215
	s_mul_i32 s16, s8, 0x180000
	s_mul_hi_u32 s17, s8, 0x180000
	s_lshl_b32 s28, s4, 9
	s_cmp_eq_u32 s5, 0
	s_cselect_b32 s29, 0, 0xfffff800
	s_cselect_b32 s35, 0x3db504f3, 1.0
	s_add_i32 s28, s28, s29
	s_add_u32 s16, s16, s28
	s_addc_u32 s17, s17, 0
	s_add_u32 s16, s16, s10
	s_addc_u32 s17, s17, s11
	v_mul_f32_e32 v136, 0xbfb8aa3b, v126
	v_mul_f32_e32 v137, 0xbfb8aa3b, v127
	v_mul_f32_e32 v138, 0xbfb8aa3b, v128
	v_mul_f32_e32 v139, 0xbfb8aa3b, v129
	v_mul_f32_e32 v140, 0xbfb8aa3b, v122
	v_mul_f32_e32 v141, 0xbfb8aa3b, v123
	v_mul_f32_e32 v142, 0xbfb8aa3b, v124
	v_mul_f32_e32 v143, 0xbfb8aa3b, v125
	v_mul_f32_e32 v144, 0xbfb8aa3b, v118
	v_mul_f32_e32 v145, 0xbfb8aa3b, v119
	v_mul_f32_e32 v146, 0xbfb8aa3b, v120
	v_mul_f32_e32 v147, 0xbfb8aa3b, v121
	v_mul_f32_e32 v148, 0xbfb8aa3b, v114
	v_mul_f32_e32 v149, 0xbfb8aa3b, v115
	v_mul_f32_e32 v150, 0xbfb8aa3b, v116
	v_mul_f32_e32 v151, 0xbfb8aa3b, v117
	v_exp_f32_e32 v136, v136
	v_exp_f32_e32 v137, v137
	v_exp_f32_e32 v138, v138
	v_exp_f32_e32 v139, v139
	v_exp_f32_e32 v140, v140
	v_exp_f32_e32 v141, v141
	v_exp_f32_e32 v142, v142
	v_exp_f32_e32 v143, v143
	v_exp_f32_e32 v144, v144
	v_exp_f32_e32 v145, v145
	v_exp_f32_e32 v146, v146
	v_exp_f32_e32 v147, v147
	v_exp_f32_e32 v148, v148
	v_exp_f32_e32 v149, v149
	v_exp_f32_e32 v150, v150
	v_exp_f32_e32 v151, v151
	v_add_f32_e32 v136, 1.0, v136
	v_add_f32_e32 v137, 1.0, v137
	v_add_f32_e32 v138, 1.0, v138
	v_add_f32_e32 v139, 1.0, v139
	v_add_f32_e32 v140, 1.0, v140
	v_add_f32_e32 v141, 1.0, v141
	v_add_f32_e32 v142, 1.0, v142
	v_add_f32_e32 v143, 1.0, v143
	v_add_f32_e32 v144, 1.0, v144
	v_add_f32_e32 v145, 1.0, v145
	v_add_f32_e32 v146, 1.0, v146
	v_add_f32_e32 v147, 1.0, v147
	v_add_f32_e32 v148, 1.0, v148
	v_add_f32_e32 v149, 1.0, v149
	v_add_f32_e32 v150, 1.0, v150
	v_add_f32_e32 v151, 1.0, v151
	v_rcp_f32_e32 v136, v136
	v_rcp_f32_e32 v137, v137
	v_rcp_f32_e32 v138, v138
	v_rcp_f32_e32 v139, v139
	v_rcp_f32_e32 v140, v140
	v_rcp_f32_e32 v141, v141
	v_rcp_f32_e32 v142, v142
	v_rcp_f32_e32 v143, v143
	v_rcp_f32_e32 v144, v144
	v_rcp_f32_e32 v145, v145
	v_rcp_f32_e32 v146, v146
	v_rcp_f32_e32 v147, v147
	v_rcp_f32_e32 v148, v148
	v_rcp_f32_e32 v149, v149
	v_rcp_f32_e32 v150, v150
	v_rcp_f32_e32 v151, v151
	v_mul_f32_e32 v126, v126, v136
	v_mul_f32_e32 v127, v127, v137
	v_mul_f32_e32 v128, v128, v138
	v_mul_f32_e32 v129, v129, v139
	v_mul_f32_e32 v122, v122, v140
	v_mul_f32_e32 v123, v123, v141
	v_mul_f32_e32 v124, v124, v142
	v_mul_f32_e32 v125, v125, v143
	v_mul_f32_e32 v118, v118, v144
	v_mul_f32_e32 v119, v119, v145
	v_mul_f32_e32 v120, v120, v146
	v_mul_f32_e32 v121, v121, v147
	v_mul_f32_e32 v114, v114, v148
	v_mul_f32_e32 v115, v115, v149
	v_mul_f32_e32 v116, v116, v150
	v_mul_f32_e32 v117, v117, v151
	v_mul_f32_e32 v126, s35, v126
	v_mul_f32_e32 v127, s35, v127
	v_mul_f32_e32 v128, s35, v128
	v_mul_f32_e32 v129, s35, v129
	v_mul_f32_e32 v122, s35, v122
	v_mul_f32_e32 v123, s35, v123
	v_mul_f32_e32 v124, s35, v124
	v_mul_f32_e32 v125, s35, v125
	v_mul_f32_e32 v118, s35, v118
	v_mul_f32_e32 v119, s35, v119
	v_mul_f32_e32 v120, s35, v120
	v_mul_f32_e32 v121, s35, v121
	v_mul_f32_e32 v114, s35, v114
	v_mul_f32_e32 v115, s35, v115
	v_mul_f32_e32 v116, s35, v116
	v_mul_f32_e32 v117, s35, v117
	v_cvt_pk_bf16_f32 v160, v126, v127
	v_cvt_pk_bf16_f32 v161, v128, v129
	v_cvt_pk_bf16_f32 v162, v122, v123
	v_cvt_pk_bf16_f32 v163, v124, v125
	v_cvt_pk_bf16_f32 v164, v118, v119
	v_cvt_pk_bf16_f32 v165, v120, v121
	v_cvt_pk_bf16_f32 v166, v114, v115
	v_cvt_pk_bf16_f32 v167, v116, v117
	ds_write_b64 v213, v[160:161]
	ds_write_b64 v213, v[162:163] offset:32
	ds_write_b64 v213, v[164:165] offset:64
	ds_write_b64 v213, v[166:167] offset:96
	ds_read2_b64 v[168:171], v214 offset1:1
	ds_read2_b64 v[172:175], v214 offset0:136 offset1:137
	s_waitcnt lgkmcnt(0)
; DI bf16_t f2bf(float a) { return (bf16_t)(pk_bf16(a, 0.f) & 0xffffu); }
; DI float silu_f(float x) { return x * __builtin_amdgcn_rcpf(1.f + __expf(-x)); }
; template <int EPI>
; DI void gemm_phase(const bf16_t* __restrict__ A, const bf16_t* __restrict__ Bt, const int K, const int N, const Params& p, const int layer_j, char* lds) {
;     ...
;             } else {
;                 const int dc0 = (region == 0) ? col0 : (col0 - 3072 + 2048);
;                 const float sc = (region == 0) ? 0.08838834764831845f : 1.0f;
;                 bf16_t* dst = PROJ + (size_t)row0 * ATT_IN + dc0 + fr;
; #pragma unroll
;                 for (int ai = 0; ai < 2; ++ai)
; #pragma unroll
;                     for (int m = 0; m < 4; ++m)
; #pragma unroll
;                         for (int j = 0; j < 4; ++j)
; #pragma unroll
;                             for (int bj = 0; bj < 2; ++bj)
; #pragma unroll
;                                 for (int n = 0; n < 2; ++n) dst[(size_t)(ai * 128 + m * 16 + j) * ATT_IN + bj * 32 + n * 16] = f2bf(silu_f(acc[ai][bj][m][n][j]) * sc);
;             }
	global_store_dwordx4 v215, v[168:171], s[16:17]
	global_store_dwordx4 v216, v[172:175], s[16:17]
	v_mul_f32_e32 v136, 0xbfb8aa3b, v110
	v_mul_f32_e32 v137, 0xbfb8aa3b, v111
	v_mul_f32_e32 v138, 0xbfb8aa3b, v112
	v_mul_f32_e32 v139, 0xbfb8aa3b, v113
	v_mul_f32_e32 v140, 0xbfb8aa3b, v106
	v_mul_f32_e32 v141, 0xbfb8aa3b, v107
	v_mul_f32_e32 v142, 0xbfb8aa3b, v108
	v_mul_f32_e32 v143, 0xbfb8aa3b, v109
	v_mul_f32_e32 v144, 0xbfb8aa3b, v102
	v_mul_f32_e32 v145, 0xbfb8aa3b, v103
	v_mul_f32_e32 v146, 0xbfb8aa3b, v104
	v_mul_f32_e32 v147, 0xbfb8aa3b, v105
	v_mul_f32_e32 v148, 0xbfb8aa3b, v98
	v_mul_f32_e32 v149, 0xbfb8aa3b, v99
	v_mul_f32_e32 v150, 0xbfb8aa3b, v100
	v_mul_f32_e32 v151, 0xbfb8aa3b, v101
	v_exp_f32_e32 v136, v136
	v_exp_f32_e32 v137, v137
	v_exp_f32_e32 v138, v138
	v_exp_f32_e32 v139, v139
	v_exp_f32_e32 v140, v140
	v_exp_f32_e32 v141, v141
	v_exp_f32_e32 v142, v142
	v_exp_f32_e32 v143, v143
	v_exp_f32_e32 v144, v144
	v_exp_f32_e32 v145, v145
	v_exp_f32_e32 v146, v146
	v_exp_f32_e32 v147, v147
	v_exp_f32_e32 v148, v148
	v_exp_f32_e32 v149, v149
	v_exp_f32_e32 v150, v150
	v_exp_f32_e32 v151, v151
	v_add_f32_e32 v136, 1.0, v136
	v_add_f32_e32 v137, 1.0, v137
	v_add_f32_e32 v138, 1.0, v138
	v_add_f32_e32 v139, 1.0, v139
	v_add_f32_e32 v140, 1.0, v140
	v_add_f32_e32 v141, 1.0, v141
	v_add_f32_e32 v142, 1.0, v142
	v_add_f32_e32 v143, 1.0, v143
	v_add_f32_e32 v144, 1.0, v144
	v_add_f32_e32 v145, 1.0, v145
	v_add_f32_e32 v146, 1.0, v146
	v_add_f32_e32 v147, 1.0, v147
	v_add_f32_e32 v148, 1.0, v148
	v_add_f32_e32 v149, 1.0, v149
	v_add_f32_e32 v150, 1.0, v150
	v_add_f32_e32 v151, 1.0, v151
	v_rcp_f32_e32 v136, v136
	v_rcp_f32_e32 v137, v137
	v_rcp_f32_e32 v138, v138
	v_rcp_f32_e32 v139, v139
	v_rcp_f32_e32 v140, v140
	v_rcp_f32_e32 v141, v141
	v_rcp_f32_e32 v142, v142
	v_rcp_f32_e32 v143, v143
	v_rcp_f32_e32 v144, v144
	v_rcp_f32_e32 v145, v145
	v_rcp_f32_e32 v146, v146
	v_rcp_f32_e32 v147, v147
	v_rcp_f32_e32 v148, v148
	v_rcp_f32_e32 v149, v149
	v_rcp_f32_e32 v150, v150
	v_rcp_f32_e32 v151, v151
	v_mul_f32_e32 v110, v110, v136
	v_mul_f32_e32 v111, v111, v137
	v_mul_f32_e32 v112, v112, v138
	v_mul_f32_e32 v113, v113, v139
	v_mul_f32_e32 v106, v106, v140
	v_mul_f32_e32 v107, v107, v141
	v_mul_f32_e32 v108, v108, v142
	v_mul_f32_e32 v109, v109, v143
	v_mul_f32_e32 v102, v102, v144
	v_mul_f32_e32 v103, v103, v145
	v_mul_f32_e32 v104, v104, v146
	v_mul_f32_e32 v105, v105, v147
	v_mul_f32_e32 v98, v98, v148
	v_mul_f32_e32 v99, v99, v149
	v_mul_f32_e32 v100, v100, v150
	v_mul_f32_e32 v101, v101, v151
	v_mul_f32_e32 v110, s35, v110
	v_mul_f32_e32 v111, s35, v111
	v_mul_f32_e32 v112, s35, v112
	v_mul_f32_e32 v113, s35, v113
	v_mul_f32_e32 v106, s35, v106
	v_mul_f32_e32 v107, s35, v107
	v_mul_f32_e32 v108, s35, v108
	v_mul_f32_e32 v109, s35, v109
	v_mul_f32_e32 v102, s35, v102
	v_mul_f32_e32 v103, s35, v103
	v_mul_f32_e32 v104, s35, v104
	v_mul_f32_e32 v105, s35, v105
	v_mul_f32_e32 v98, s35, v98
	v_mul_f32_e32 v99, s35, v99
	v_mul_f32_e32 v100, s35, v100
	v_mul_f32_e32 v101, s35, v101
	v_cvt_pk_bf16_f32 v160, v110, v111
	v_cvt_pk_bf16_f32 v161, v112, v113
	v_cvt_pk_bf16_f32 v162, v106, v107
	v_cvt_pk_bf16_f32 v163, v108, v109
	v_cvt_pk_bf16_f32 v164, v102, v103
	v_cvt_pk_bf16_f32 v165, v104, v105
	v_cvt_pk_bf16_f32 v166, v98, v99
	v_cvt_pk_bf16_f32 v167, v100, v101
	ds_write_b64 v213, v[160:161]
	ds_write_b64 v213, v[162:163] offset:32
	ds_write_b64 v213, v[164:165] offset:64
	ds_write_b64 v213, v[166:167] offset:96
	ds_read2_b64 v[168:171], v214 offset1:1
	ds_read2_b64 v[172:175], v214 offset0:136 offset1:137
	v_add_u32_e32 v217, 0x18000, v215
	v_add_u32_e32 v218, 0x18000, v216
	s_waitcnt lgkmcnt(0)
	global_store_dwordx4 v217, v[168:171], s[16:17]
	global_store_dwordx4 v218, v[172:175], s[16:17]
	v_mul_f32_e32 v136, 0xbfb8aa3b, v94
	v_mul_f32_e32 v137, 0xbfb8aa3b, v95
	v_mul_f32_e32 v138, 0xbfb8aa3b, v96
	v_mul_f32_e32 v139, 0xbfb8aa3b, v97
	v_mul_f32_e32 v140, 0xbfb8aa3b, v90
	v_mul_f32_e32 v141, 0xbfb8aa3b, v91
	v_mul_f32_e32 v142, 0xbfb8aa3b, v92
	v_mul_f32_e32 v143, 0xbfb8aa3b, v93
	v_mul_f32_e32 v144, 0xbfb8aa3b, v86
	v_mul_f32_e32 v145, 0xbfb8aa3b, v87
	v_mul_f32_e32 v146, 0xbfb8aa3b, v88
	v_mul_f32_e32 v147, 0xbfb8aa3b, v89
	v_mul_f32_e32 v148, 0xbfb8aa3b, v82
	v_mul_f32_e32 v149, 0xbfb8aa3b, v83
	v_mul_f32_e32 v150, 0xbfb8aa3b, v84
	v_mul_f32_e32 v151, 0xbfb8aa3b, v85
	v_exp_f32_e32 v136, v136
	v_exp_f32_e32 v137, v137
	v_exp_f32_e32 v138, v138
	v_exp_f32_e32 v139, v139
	v_exp_f32_e32 v140, v140
	v_exp_f32_e32 v141, v141
	v_exp_f32_e32 v142, v142
	v_exp_f32_e32 v143, v143
	v_exp_f32_e32 v144, v144
	v_exp_f32_e32 v145, v145
	v_exp_f32_e32 v146, v146
	v_exp_f32_e32 v147, v147
	v_exp_f32_e32 v148, v148
	v_exp_f32_e32 v149, v149
	v_exp_f32_e32 v150, v150
	v_exp_f32_e32 v151, v151
	v_add_f32_e32 v136, 1.0, v136
	v_add_f32_e32 v137, 1.0, v137
	v_add_f32_e32 v138, 1.0, v138
	v_add_f32_e32 v139, 1.0, v139
	v_add_f32_e32 v140, 1.0, v140
	v_add_f32_e32 v141, 1.0, v141
	v_add_f32_e32 v142, 1.0, v142
	v_add_f32_e32 v143, 1.0, v143
	v_add_f32_e32 v144, 1.0, v144
	v_add_f32_e32 v145, 1.0, v145
	v_add_f32_e32 v146, 1.0, v146
	v_add_f32_e32 v147, 1.0, v147
	v_add_f32_e32 v148, 1.0, v148
	v_add_f32_e32 v149, 1.0, v149
	v_add_f32_e32 v150, 1.0, v150
	v_add_f32_e32 v151, 1.0, v151
	v_rcp_f32_e32 v136, v136
	v_rcp_f32_e32 v137, v137
	v_rcp_f32_e32 v138, v138
	v_rcp_f32_e32 v139, v139
	v_rcp_f32_e32 v140, v140
	v_rcp_f32_e32 v141, v141
	v_rcp_f32_e32 v142, v142
	v_rcp_f32_e32 v143, v143
	v_rcp_f32_e32 v144, v144
	v_rcp_f32_e32 v145, v145
	v_rcp_f32_e32 v146, v146
	v_rcp_f32_e32 v147, v147
	v_rcp_f32_e32 v148, v148
	v_rcp_f32_e32 v149, v149
	v_rcp_f32_e32 v150, v150
; DI bf16_t f2bf(float a) { return (bf16_t)(pk_bf16(a, 0.f) & 0xffffu); }
; DI float silu_f(float x) { return x * __builtin_amdgcn_rcpf(1.f + __expf(-x)); }
; template <int EPI>
; DI void gemm_phase(const bf16_t* __restrict__ A, const bf16_t* __restrict__ Bt, const int K, const int N, const Params& p, const int layer_j, char* lds) {
;     ...
;             } else {
;                 const int dc0 = (region == 0) ? col0 : (col0 - 3072 + 2048);
;                 const float sc = (region == 0) ? 0.08838834764831845f : 1.0f;
;                 bf16_t* dst = PROJ + (size_t)row0 * ATT_IN + dc0 + fr;
; #pragma unroll
;                 for (int ai = 0; ai < 2; ++ai)
; #pragma unroll
;                     for (int m = 0; m < 4; ++m)
; #pragma unroll
;                         for (int j = 0; j < 4; ++j)
; #pragma unroll
;                             for (int bj = 0; bj < 2; ++bj)
; #pragma unroll
;                                 for (int n = 0; n < 2; ++n) dst[(size_t)(ai * 128 + m * 16 + j) * ATT_IN + bj * 32 + n * 16] = f2bf(silu_f(acc[ai][bj][m][n][j]) * sc);
;             }
	v_rcp_f32_e32 v151, v151
	v_mul_f32_e32 v94, v94, v136
	v_mul_f32_e32 v95, v95, v137
	v_mul_f32_e32 v96, v96, v138
	v_mul_f32_e32 v97, v97, v139
	v_mul_f32_e32 v90, v90, v140
	v_mul_f32_e32 v91, v91, v141
	v_mul_f32_e32 v92, v92, v142
	v_mul_f32_e32 v93, v93, v143
	v_mul_f32_e32 v86, v86, v144
	v_mul_f32_e32 v87, v87, v145
	v_mul_f32_e32 v88, v88, v146
	v_mul_f32_e32 v89, v89, v147
	v_mul_f32_e32 v82, v82, v148
	v_mul_f32_e32 v83, v83, v149
	v_mul_f32_e32 v84, v84, v150
	v_mul_f32_e32 v85, v85, v151
	v_mul_f32_e32 v94, s35, v94
	v_mul_f32_e32 v95, s35, v95
	v_mul_f32_e32 v96, s35, v96
	v_mul_f32_e32 v97, s35, v97
	v_mul_f32_e32 v90, s35, v90
	v_mul_f32_e32 v91, s35, v91
	v_mul_f32_e32 v92, s35, v92
	v_mul_f32_e32 v93, s35, v93
	v_mul_f32_e32 v86, s35, v86
	v_mul_f32_e32 v87, s35, v87
	v_mul_f32_e32 v88, s35, v88
	v_mul_f32_e32 v89, s35, v89
	v_mul_f32_e32 v82, s35, v82
	v_mul_f32_e32 v83, s35, v83
	v_mul_f32_e32 v84, s35, v84
	v_mul_f32_e32 v85, s35, v85
	v_cvt_pk_bf16_f32 v160, v94, v95
	v_cvt_pk_bf16_f32 v161, v96, v97
	v_cvt_pk_bf16_f32 v162, v90, v91
	v_cvt_pk_bf16_f32 v163, v92, v93
	v_cvt_pk_bf16_f32 v164, v86, v87
	v_cvt_pk_bf16_f32 v165, v88, v89
	v_cvt_pk_bf16_f32 v166, v82, v83
	v_cvt_pk_bf16_f32 v167, v84, v85
	ds_write_b64 v213, v[160:161]
	ds_write_b64 v213, v[162:163] offset:32
	ds_write_b64 v213, v[164:165] offset:64
	ds_write_b64 v213, v[166:167] offset:96
	ds_read2_b64 v[168:171], v214 offset1:1
	ds_read2_b64 v[172:175], v214 offset0:136 offset1:137
	v_add_u32_e32 v217, 0x30000, v215
	v_add_u32_e32 v218, 0x30000, v216
	s_waitcnt lgkmcnt(0)
	global_store_dwordx4 v217, v[168:171], s[16:17]
	global_store_dwordx4 v218, v[172:175], s[16:17]
	v_mul_f32_e32 v136, 0xbfb8aa3b, v78
	v_mul_f32_e32 v137, 0xbfb8aa3b, v79
	v_mul_f32_e32 v138, 0xbfb8aa3b, v80
	v_mul_f32_e32 v139, 0xbfb8aa3b, v81
	v_mul_f32_e32 v140, 0xbfb8aa3b, v74
	v_mul_f32_e32 v141, 0xbfb8aa3b, v75
	v_mul_f32_e32 v142, 0xbfb8aa3b, v76
	v_mul_f32_e32 v143, 0xbfb8aa3b, v77
	v_mul_f32_e32 v144, 0xbfb8aa3b, v38
	v_mul_f32_e32 v145, 0xbfb8aa3b, v39
	v_mul_f32_e32 v146, 0xbfb8aa3b, v40
	v_mul_f32_e32 v147, 0xbfb8aa3b, v41
	v_mul_f32_e32 v148, 0xbfb8aa3b, v16
	v_mul_f32_e32 v149, 0xbfb8aa3b, v17
	v_mul_f32_e32 v150, 0xbfb8aa3b, v18
	v_mul_f32_e32 v151, 0xbfb8aa3b, v19
	v_exp_f32_e32 v136, v136
	v_exp_f32_e32 v137, v137
	v_exp_f32_e32 v138, v138
	v_exp_f32_e32 v139, v139
	v_exp_f32_e32 v140, v140
	v_exp_f32_e32 v141, v141
	v_exp_f32_e32 v142, v142
	v_exp_f32_e32 v143, v143
	v_exp_f32_e32 v144, v144
	v_exp_f32_e32 v145, v145
	v_exp_f32_e32 v146, v146
	v_exp_f32_e32 v147, v147
	v_exp_f32_e32 v148, v148
	v_exp_f32_e32 v149, v149
	v_exp_f32_e32 v150, v150
	v_exp_f32_e32 v151, v151
	v_add_f32_e32 v136, 1.0, v136
	v_add_f32_e32 v137, 1.0, v137
	v_add_f32_e32 v138, 1.0, v138
	v_add_f32_e32 v139, 1.0, v139
	v_add_f32_e32 v140, 1.0, v140
	v_add_f32_e32 v141, 1.0, v141
	v_add_f32_e32 v142, 1.0, v142
	v_add_f32_e32 v143, 1.0, v143
	v_add_f32_e32 v144, 1.0, v144
	v_add_f32_e32 v145, 1.0, v145
	v_add_f32_e32 v146, 1.0, v146
	v_add_f32_e32 v147, 1.0, v147
	v_add_f32_e32 v148, 1.0, v148
	v_add_f32_e32 v149, 1.0, v149
	v_add_f32_e32 v150, 1.0, v150
	v_add_f32_e32 v151, 1.0, v151
	v_rcp_f32_e32 v136, v136
	v_rcp_f32_e32 v137, v137
	v_rcp_f32_e32 v138, v138
	v_rcp_f32_e32 v139, v139
	v_rcp_f32_e32 v140, v140
	v_rcp_f32_e32 v141, v141
	v_rcp_f32_e32 v142, v142
	v_rcp_f32_e32 v143, v143
	v_rcp_f32_e32 v144, v144
	v_rcp_f32_e32 v145, v145
	v_rcp_f32_e32 v146, v146
	v_rcp_f32_e32 v147, v147
	v_rcp_f32_e32 v148, v148
	v_rcp_f32_e32 v149, v149
	v_rcp_f32_e32 v150, v150
	v_rcp_f32_e32 v151, v151
	v_mul_f32_e32 v78, v78, v136
	v_mul_f32_e32 v79, v79, v137
	v_mul_f32_e32 v80, v80, v138
	v_mul_f32_e32 v81, v81, v139
	v_mul_f32_e32 v74, v74, v140
	v_mul_f32_e32 v75, v75, v141
	v_mul_f32_e32 v76, v76, v142
	v_mul_f32_e32 v77, v77, v143
	v_mul_f32_e32 v38, v38, v144
	v_mul_f32_e32 v39, v39, v145
	v_mul_f32_e32 v40, v40, v146
	v_mul_f32_e32 v41, v41, v147
	v_mul_f32_e32 v16, v16, v148
	v_mul_f32_e32 v17, v17, v149
	v_mul_f32_e32 v18, v18, v150
	v_mul_f32_e32 v19, v19, v151
	v_mul_f32_e32 v78, s35, v78
	v_mul_f32_e32 v79, s35, v79
	v_mul_f32_e32 v80, s35, v80
	v_mul_f32_e32 v81, s35, v81
	v_mul_f32_e32 v74, s35, v74
	v_mul_f32_e32 v75, s35, v75
	v_mul_f32_e32 v76, s35, v76
	v_mul_f32_e32 v77, s35, v77
	v_mul_f32_e32 v38, s35, v38
	v_mul_f32_e32 v39, s35, v39
	v_mul_f32_e32 v40, s35, v40
	v_mul_f32_e32 v41, s35, v41
	v_mul_f32_e32 v16, s35, v16
	v_mul_f32_e32 v17, s35, v17
	v_mul_f32_e32 v18, s35, v18
	v_mul_f32_e32 v19, s35, v19
	v_cvt_pk_bf16_f32 v160, v78, v79
	v_cvt_pk_bf16_f32 v161, v80, v81
	v_cvt_pk_bf16_f32 v162, v74, v75
	v_cvt_pk_bf16_f32 v163, v76, v77
	v_cvt_pk_bf16_f32 v164, v38, v39
	v_cvt_pk_bf16_f32 v165, v40, v41
	v_cvt_pk_bf16_f32 v166, v16, v17
	v_cvt_pk_bf16_f32 v167, v18, v19
	ds_write_b64 v213, v[160:161]
	ds_write_b64 v213, v[162:163] offset:32
	ds_write_b64 v213, v[164:165] offset:64
	ds_write_b64 v213, v[166:167] offset:96
	ds_read2_b64 v[168:171], v214 offset1:1
	ds_read2_b64 v[172:175], v214 offset0:136 offset1:137
	v_add_u32_e32 v217, 0x48000, v215
	v_add_u32_e32 v218, 0x48000, v216
	s_waitcnt lgkmcnt(0)
; DI bf16_t f2bf(float a) { return (bf16_t)(pk_bf16(a, 0.f) & 0xffffu); }
; DI float silu_f(float x) { return x * __builtin_amdgcn_rcpf(1.f + __expf(-x)); }
; template <int EPI>
; DI void gemm_phase(const bf16_t* __restrict__ A, const bf16_t* __restrict__ Bt, const int K, const int N, const Params& p, const int layer_j, char* lds) {
;     ...
;             } else {
;                 const int dc0 = (region == 0) ? col0 : (col0 - 3072 + 2048);
;                 const float sc = (region == 0) ? 0.08838834764831845f : 1.0f;
;                 bf16_t* dst = PROJ + (size_t)row0 * ATT_IN + dc0 + fr;
; #pragma unroll
;                 for (int ai = 0; ai < 2; ++ai)
; #pragma unroll
;                     for (int m = 0; m < 4; ++m)
; #pragma unroll
;                         for (int j = 0; j < 4; ++j)
; #pragma unroll
;                             for (int bj = 0; bj < 2; ++bj)
; #pragma unroll
;                                 for (int n = 0; n < 2; ++n) dst[(size_t)(ai * 128 + m * 16 + j) * ATT_IN + bj * 32 + n * 16] = f2bf(silu_f(acc[ai][bj][m][n][j]) * sc);
;             }
	global_store_dwordx4 v217, v[168:171], s[16:17]
	global_store_dwordx4 v218, v[172:175], s[16:17]
	v_mul_f32_e32 v136, 0xbfb8aa3b, v70
	v_mul_f32_e32 v137, 0xbfb8aa3b, v71
	v_mul_f32_e32 v138, 0xbfb8aa3b, v72
	v_mul_f32_e32 v139, 0xbfb8aa3b, v73
	v_mul_f32_e32 v140, 0xbfb8aa3b, v54
	v_mul_f32_e32 v141, 0xbfb8aa3b, v55
	v_mul_f32_e32 v142, 0xbfb8aa3b, v56
	v_mul_f32_e32 v143, 0xbfb8aa3b, v57
	v_mul_f32_e32 v144, 0xbfb8aa3b, v34
	v_mul_f32_e32 v145, 0xbfb8aa3b, v35
	v_mul_f32_e32 v146, 0xbfb8aa3b, v36
	v_mul_f32_e32 v147, 0xbfb8aa3b, v37
	v_mul_f32_e32 v148, 0xbfb8aa3b, v12
	v_mul_f32_e32 v149, 0xbfb8aa3b, v13
	v_mul_f32_e32 v150, 0xbfb8aa3b, v14
	v_mul_f32_e32 v151, 0xbfb8aa3b, v15
	v_exp_f32_e32 v136, v136
	v_exp_f32_e32 v137, v137
	v_exp_f32_e32 v138, v138
	v_exp_f32_e32 v139, v139
	v_exp_f32_e32 v140, v140
	v_exp_f32_e32 v141, v141
	v_exp_f32_e32 v142, v142
	v_exp_f32_e32 v143, v143
	v_exp_f32_e32 v144, v144
	v_exp_f32_e32 v145, v145
	v_exp_f32_e32 v146, v146
	v_exp_f32_e32 v147, v147
	v_exp_f32_e32 v148, v148
	v_exp_f32_e32 v149, v149
	v_exp_f32_e32 v150, v150
	v_exp_f32_e32 v151, v151
	v_add_f32_e32 v136, 1.0, v136
	v_add_f32_e32 v137, 1.0, v137
	v_add_f32_e32 v138, 1.0, v138
	v_add_f32_e32 v139, 1.0, v139
	v_add_f32_e32 v140, 1.0, v140
	v_add_f32_e32 v141, 1.0, v141
	v_add_f32_e32 v142, 1.0, v142
	v_add_f32_e32 v143, 1.0, v143
	v_add_f32_e32 v144, 1.0, v144
	v_add_f32_e32 v145, 1.0, v145
	v_add_f32_e32 v146, 1.0, v146
	v_add_f32_e32 v147, 1.0, v147
	v_add_f32_e32 v148, 1.0, v148
	v_add_f32_e32 v149, 1.0, v149
	v_add_f32_e32 v150, 1.0, v150
	v_add_f32_e32 v151, 1.0, v151
	v_rcp_f32_e32 v136, v136
	v_rcp_f32_e32 v137, v137
	v_rcp_f32_e32 v138, v138
	v_rcp_f32_e32 v139, v139
	v_rcp_f32_e32 v140, v140
	v_rcp_f32_e32 v141, v141
	v_rcp_f32_e32 v142, v142
	v_rcp_f32_e32 v143, v143
	v_rcp_f32_e32 v144, v144
	v_rcp_f32_e32 v145, v145
	v_rcp_f32_e32 v146, v146
	v_rcp_f32_e32 v147, v147
	v_rcp_f32_e32 v148, v148
	v_rcp_f32_e32 v149, v149
	v_rcp_f32_e32 v150, v150
	v_rcp_f32_e32 v151, v151
	v_mul_f32_e32 v70, v70, v136
	v_mul_f32_e32 v71, v71, v137
	v_mul_f32_e32 v72, v72, v138
	v_mul_f32_e32 v73, v73, v139
	v_mul_f32_e32 v54, v54, v140
	v_mul_f32_e32 v55, v55, v141
	v_mul_f32_e32 v56, v56, v142
	v_mul_f32_e32 v57, v57, v143
	v_mul_f32_e32 v34, v34, v144
	v_mul_f32_e32 v35, v35, v145
	v_mul_f32_e32 v36, v36, v146
	v_mul_f32_e32 v37, v37, v147
	v_mul_f32_e32 v12, v12, v148
	v_mul_f32_e32 v13, v13, v149
	v_mul_f32_e32 v14, v14, v150
	v_mul_f32_e32 v15, v15, v151
	v_mul_f32_e32 v70, s35, v70
	v_mul_f32_e32 v71, s35, v71
	v_mul_f32_e32 v72, s35, v72
	v_mul_f32_e32 v73, s35, v73
	v_mul_f32_e32 v54, s35, v54
	v_mul_f32_e32 v55, s35, v55
	v_mul_f32_e32 v56, s35, v56
	v_mul_f32_e32 v57, s35, v57
	v_mul_f32_e32 v34, s35, v34
	v_mul_f32_e32 v35, s35, v35
	v_mul_f32_e32 v36, s35, v36
	v_mul_f32_e32 v37, s35, v37
	v_mul_f32_e32 v12, s35, v12
	v_mul_f32_e32 v13, s35, v13
	v_mul_f32_e32 v14, s35, v14
	v_mul_f32_e32 v15, s35, v15
	v_cvt_pk_bf16_f32 v160, v70, v71
	v_cvt_pk_bf16_f32 v161, v72, v73
	v_cvt_pk_bf16_f32 v162, v54, v55
	v_cvt_pk_bf16_f32 v163, v56, v57
	v_cvt_pk_bf16_f32 v164, v34, v35
	v_cvt_pk_bf16_f32 v165, v36, v37
	v_cvt_pk_bf16_f32 v166, v12, v13
	v_cvt_pk_bf16_f32 v167, v14, v15
	ds_write_b64 v213, v[160:161]
	ds_write_b64 v213, v[162:163] offset:32
	ds_write_b64 v213, v[164:165] offset:64
	ds_write_b64 v213, v[166:167] offset:96
	ds_read2_b64 v[168:171], v214 offset1:1
	ds_read2_b64 v[172:175], v214 offset0:136 offset1:137
	v_add_u32_e32 v217, 0xc0000, v215
	v_add_u32_e32 v218, 0xc0000, v216
	s_waitcnt lgkmcnt(0)
	global_store_dwordx4 v217, v[168:171], s[16:17]
	global_store_dwordx4 v218, v[172:175], s[16:17]
	v_mul_f32_e32 v136, 0xbfb8aa3b, v66
	v_mul_f32_e32 v137, 0xbfb8aa3b, v67
	v_mul_f32_e32 v138, 0xbfb8aa3b, v68
	v_mul_f32_e32 v139, 0xbfb8aa3b, v69
	v_mul_f32_e32 v140, 0xbfb8aa3b, v50
	v_mul_f32_e32 v141, 0xbfb8aa3b, v51
	v_mul_f32_e32 v142, 0xbfb8aa3b, v52
	v_mul_f32_e32 v143, 0xbfb8aa3b, v53
	v_mul_f32_e32 v144, 0xbfb8aa3b, v28
	v_mul_f32_e32 v145, 0xbfb8aa3b, v29
	v_mul_f32_e32 v146, 0xbfb8aa3b, v30
	v_mul_f32_e32 v147, 0xbfb8aa3b, v31
	v_mul_f32_e32 v148, 0xbfb8aa3b, v8
	v_mul_f32_e32 v149, 0xbfb8aa3b, v9
	v_mul_f32_e32 v150, 0xbfb8aa3b, v10
	v_mul_f32_e32 v151, 0xbfb8aa3b, v11
	v_exp_f32_e32 v136, v136
	v_exp_f32_e32 v137, v137
	v_exp_f32_e32 v138, v138
	v_exp_f32_e32 v139, v139
	v_exp_f32_e32 v140, v140
	v_exp_f32_e32 v141, v141
	v_exp_f32_e32 v142, v142
	v_exp_f32_e32 v143, v143
	v_exp_f32_e32 v144, v144
	v_exp_f32_e32 v145, v145
	v_exp_f32_e32 v146, v146
	v_exp_f32_e32 v147, v147
	v_exp_f32_e32 v148, v148
	v_exp_f32_e32 v149, v149
	v_exp_f32_e32 v150, v150
	v_exp_f32_e32 v151, v151
	v_add_f32_e32 v136, 1.0, v136
	v_add_f32_e32 v137, 1.0, v137
	v_add_f32_e32 v138, 1.0, v138
	v_add_f32_e32 v139, 1.0, v139
	v_add_f32_e32 v140, 1.0, v140
	v_add_f32_e32 v141, 1.0, v141
	v_add_f32_e32 v142, 1.0, v142
	v_add_f32_e32 v143, 1.0, v143
	v_add_f32_e32 v144, 1.0, v144
	v_add_f32_e32 v145, 1.0, v145
	v_add_f32_e32 v146, 1.0, v146
	v_add_f32_e32 v147, 1.0, v147
	v_add_f32_e32 v148, 1.0, v148
	v_add_f32_e32 v149, 1.0, v149
	v_add_f32_e32 v150, 1.0, v150
	v_add_f32_e32 v151, 1.0, v151
	v_rcp_f32_e32 v136, v136
	v_rcp_f32_e32 v137, v137
	v_rcp_f32_e32 v138, v138
	v_rcp_f32_e32 v139, v139
	v_rcp_f32_e32 v140, v140
	v_rcp_f32_e32 v141, v141
	v_rcp_f32_e32 v142, v142
	v_rcp_f32_e32 v143, v143
	v_rcp_f32_e32 v144, v144
	v_rcp_f32_e32 v145, v145
	v_rcp_f32_e32 v146, v146
	v_rcp_f32_e32 v147, v147
	v_rcp_f32_e32 v148, v148
	v_rcp_f32_e32 v149, v149
	v_rcp_f32_e32 v150, v150
	v_rcp_f32_e32 v151, v151
	v_mul_f32_e32 v66, v66, v136
	v_mul_f32_e32 v67, v67, v137
; DI bf16_t f2bf(float a) { return (bf16_t)(pk_bf16(a, 0.f) & 0xffffu); }
; DI float silu_f(float x) { return x * __builtin_amdgcn_rcpf(1.f + __expf(-x)); }
; template <int EPI>
; DI void gemm_phase(const bf16_t* __restrict__ A, const bf16_t* __restrict__ Bt, const int K, const int N, const Params& p, const int layer_j, char* lds) {
;     ...
;             } else {
;                 const int dc0 = (region == 0) ? col0 : (col0 - 3072 + 2048);
;                 const float sc = (region == 0) ? 0.08838834764831845f : 1.0f;
;                 bf16_t* dst = PROJ + (size_t)row0 * ATT_IN + dc0 + fr;
; #pragma unroll
;                 for (int ai = 0; ai < 2; ++ai)
; #pragma unroll
;                     for (int m = 0; m < 4; ++m)
; #pragma unroll
;                         for (int j = 0; j < 4; ++j)
; #pragma unroll
;                             for (int bj = 0; bj < 2; ++bj)
; #pragma unroll
;                                 for (int n = 0; n < 2; ++n) dst[(size_t)(ai * 128 + m * 16 + j) * ATT_IN + bj * 32 + n * 16] = f2bf(silu_f(acc[ai][bj][m][n][j]) * sc);
;             }
	v_mul_f32_e32 v68, v68, v138
	v_mul_f32_e32 v69, v69, v139
	v_mul_f32_e32 v50, v50, v140
	v_mul_f32_e32 v51, v51, v141
	v_mul_f32_e32 v52, v52, v142
	v_mul_f32_e32 v53, v53, v143
	v_mul_f32_e32 v28, v28, v144
	v_mul_f32_e32 v29, v29, v145
	v_mul_f32_e32 v30, v30, v146
	v_mul_f32_e32 v31, v31, v147
	v_mul_f32_e32 v8, v8, v148
	v_mul_f32_e32 v9, v9, v149
	v_mul_f32_e32 v10, v10, v150
	v_mul_f32_e32 v11, v11, v151
	v_mul_f32_e32 v66, s35, v66
	v_mul_f32_e32 v67, s35, v67
	v_mul_f32_e32 v68, s35, v68
	v_mul_f32_e32 v69, s35, v69
	v_mul_f32_e32 v50, s35, v50
	v_mul_f32_e32 v51, s35, v51
	v_mul_f32_e32 v52, s35, v52
	v_mul_f32_e32 v53, s35, v53
	v_mul_f32_e32 v28, s35, v28
	v_mul_f32_e32 v29, s35, v29
	v_mul_f32_e32 v30, s35, v30
	v_mul_f32_e32 v31, s35, v31
	v_mul_f32_e32 v8, s35, v8
	v_mul_f32_e32 v9, s35, v9
	v_mul_f32_e32 v10, s35, v10
	v_mul_f32_e32 v11, s35, v11
	v_cvt_pk_bf16_f32 v160, v66, v67
	v_cvt_pk_bf16_f32 v161, v68, v69
	v_cvt_pk_bf16_f32 v162, v50, v51
	v_cvt_pk_bf16_f32 v163, v52, v53
	v_cvt_pk_bf16_f32 v164, v28, v29
	v_cvt_pk_bf16_f32 v165, v30, v31
	v_cvt_pk_bf16_f32 v166, v8, v9
	v_cvt_pk_bf16_f32 v167, v10, v11
	ds_write_b64 v213, v[160:161]
	ds_write_b64 v213, v[162:163] offset:32
	ds_write_b64 v213, v[164:165] offset:64
	ds_write_b64 v213, v[166:167] offset:96
	ds_read2_b64 v[168:171], v214 offset1:1
	ds_read2_b64 v[172:175], v214 offset0:136 offset1:137
	v_add_u32_e32 v217, 0xd8000, v215
	v_add_u32_e32 v218, 0xd8000, v216
	s_waitcnt lgkmcnt(0)
	global_store_dwordx4 v217, v[168:171], s[16:17]
	global_store_dwordx4 v218, v[172:175], s[16:17]
	v_mul_f32_e32 v136, 0xbfb8aa3b, v62
	v_mul_f32_e32 v137, 0xbfb8aa3b, v63
	v_mul_f32_e32 v138, 0xbfb8aa3b, v64
	v_mul_f32_e32 v139, 0xbfb8aa3b, v65
	v_mul_f32_e32 v140, 0xbfb8aa3b, v46
	v_mul_f32_e32 v141, 0xbfb8aa3b, v47
	v_mul_f32_e32 v142, 0xbfb8aa3b, v48
	v_mul_f32_e32 v143, 0xbfb8aa3b, v49
	v_mul_f32_e32 v144, 0xbfb8aa3b, v24
	v_mul_f32_e32 v145, 0xbfb8aa3b, v25
	v_mul_f32_e32 v146, 0xbfb8aa3b, v26
	v_mul_f32_e32 v147, 0xbfb8aa3b, v27
	v_mul_f32_e32 v148, 0xbfb8aa3b, v4
	v_mul_f32_e32 v149, 0xbfb8aa3b, v5
	v_mul_f32_e32 v150, 0xbfb8aa3b, v6
	v_mul_f32_e32 v151, 0xbfb8aa3b, v7
	v_exp_f32_e32 v136, v136
	v_exp_f32_e32 v137, v137
	v_exp_f32_e32 v138, v138
	v_exp_f32_e32 v139, v139
	v_exp_f32_e32 v140, v140
	v_exp_f32_e32 v141, v141
	v_exp_f32_e32 v142, v142
	v_exp_f32_e32 v143, v143
	v_exp_f32_e32 v144, v144
	v_exp_f32_e32 v145, v145
	v_exp_f32_e32 v146, v146
	v_exp_f32_e32 v147, v147
	v_exp_f32_e32 v148, v148
	v_exp_f32_e32 v149, v149
	v_exp_f32_e32 v150, v150
	v_exp_f32_e32 v151, v151
	v_add_f32_e32 v136, 1.0, v136
	v_add_f32_e32 v137, 1.0, v137
	v_add_f32_e32 v138, 1.0, v138
	v_add_f32_e32 v139, 1.0, v139
	v_add_f32_e32 v140, 1.0, v140
	v_add_f32_e32 v141, 1.0, v141
	v_add_f32_e32 v142, 1.0, v142
	v_add_f32_e32 v143, 1.0, v143
	v_add_f32_e32 v144, 1.0, v144
	v_add_f32_e32 v145, 1.0, v145
	v_add_f32_e32 v146, 1.0, v146
	v_add_f32_e32 v147, 1.0, v147
	v_add_f32_e32 v148, 1.0, v148
	v_add_f32_e32 v149, 1.0, v149
	v_add_f32_e32 v150, 1.0, v150
	v_add_f32_e32 v151, 1.0, v151
	v_rcp_f32_e32 v136, v136
	v_rcp_f32_e32 v137, v137
	v_rcp_f32_e32 v138, v138
	v_rcp_f32_e32 v139, v139
	v_rcp_f32_e32 v140, v140
	v_rcp_f32_e32 v141, v141
	v_rcp_f32_e32 v142, v142
	v_rcp_f32_e32 v143, v143
	v_rcp_f32_e32 v144, v144
	v_rcp_f32_e32 v145, v145
	v_rcp_f32_e32 v146, v146
	v_rcp_f32_e32 v147, v147
	v_rcp_f32_e32 v148, v148
	v_rcp_f32_e32 v149, v149
	v_rcp_f32_e32 v150, v150
	v_rcp_f32_e32 v151, v151
	v_mul_f32_e32 v62, v62, v136
	v_mul_f32_e32 v63, v63, v137
	v_mul_f32_e32 v64, v64, v138
	v_mul_f32_e32 v65, v65, v139
	v_mul_f32_e32 v46, v46, v140
	v_mul_f32_e32 v47, v47, v141
	v_mul_f32_e32 v48, v48, v142
	v_mul_f32_e32 v49, v49, v143
	v_mul_f32_e32 v24, v24, v144
	v_mul_f32_e32 v25, v25, v145
	v_mul_f32_e32 v26, v26, v146
	v_mul_f32_e32 v27, v27, v147
	v_mul_f32_e32 v4, v4, v148
	v_mul_f32_e32 v5, v5, v149
	v_mul_f32_e32 v6, v6, v150
	v_mul_f32_e32 v7, v7, v151
	v_mul_f32_e32 v62, s35, v62
	v_mul_f32_e32 v63, s35, v63
	v_mul_f32_e32 v64, s35, v64
	v_mul_f32_e32 v65, s35, v65
	v_mul_f32_e32 v46, s35, v46
	v_mul_f32_e32 v47, s35, v47
	v_mul_f32_e32 v48, s35, v48
	v_mul_f32_e32 v49, s35, v49
	v_mul_f32_e32 v24, s35, v24
	v_mul_f32_e32 v25, s35, v25
	v_mul_f32_e32 v26, s35, v26
	v_mul_f32_e32 v27, s35, v27
	v_mul_f32_e32 v4, s35, v4
	v_mul_f32_e32 v5, s35, v5
	v_mul_f32_e32 v6, s35, v6
	v_mul_f32_e32 v7, s35, v7
	v_cvt_pk_bf16_f32 v160, v62, v63
	v_cvt_pk_bf16_f32 v161, v64, v65
	v_cvt_pk_bf16_f32 v162, v46, v47
	v_cvt_pk_bf16_f32 v163, v48, v49
	v_cvt_pk_bf16_f32 v164, v24, v25
	v_cvt_pk_bf16_f32 v165, v26, v27
	v_cvt_pk_bf16_f32 v166, v4, v5
	v_cvt_pk_bf16_f32 v167, v6, v7
	ds_write_b64 v213, v[160:161]
	ds_write_b64 v213, v[162:163] offset:32
	ds_write_b64 v213, v[164:165] offset:64
	ds_write_b64 v213, v[166:167] offset:96
	ds_read2_b64 v[168:171], v214 offset1:1
	ds_read2_b64 v[172:175], v214 offset0:136 offset1:137
	v_add_u32_e32 v217, 0xf0000, v215
	v_add_u32_e32 v218, 0xf0000, v216
	s_waitcnt lgkmcnt(0)
; DI bf16_t f2bf(float a) { return (bf16_t)(pk_bf16(a, 0.f) & 0xffffu); }
; DI float silu_f(float x) { return x * __builtin_amdgcn_rcpf(1.f + __expf(-x)); }
; template <int EPI>
; DI void gemm_phase(const bf16_t* __restrict__ A, const bf16_t* __restrict__ Bt, const int K, const int N, const Params& p, const int layer_j, char* lds) {
;     ...
;             } else {
;                 const int dc0 = (region == 0) ? col0 : (col0 - 3072 + 2048);
;                 const float sc = (region == 0) ? 0.08838834764831845f : 1.0f;
;                 bf16_t* dst = PROJ + (size_t)row0 * ATT_IN + dc0 + fr;
; #pragma unroll
;                 for (int ai = 0; ai < 2; ++ai)
; #pragma unroll
;                     for (int m = 0; m < 4; ++m)
; #pragma unroll
;                         for (int j = 0; j < 4; ++j)
; #pragma unroll
;                             for (int bj = 0; bj < 2; ++bj)
; #pragma unroll
;                                 for (int n = 0; n < 2; ++n) dst[(size_t)(ai * 128 + m * 16 + j) * ATT_IN + bj * 32 + n * 16] = f2bf(silu_f(acc[ai][bj][m][n][j]) * sc);
;             }
	global_store_dwordx4 v217, v[168:171], s[16:17]
	global_store_dwordx4 v218, v[172:175], s[16:17]
	v_mul_f32_e32 v136, 0xbfb8aa3b, v58
	v_mul_f32_e32 v137, 0xbfb8aa3b, v59
	v_mul_f32_e32 v138, 0xbfb8aa3b, v60
	v_mul_f32_e32 v139, 0xbfb8aa3b, v61
	v_mul_f32_e32 v140, 0xbfb8aa3b, v42
	v_mul_f32_e32 v141, 0xbfb8aa3b, v43
	v_mul_f32_e32 v142, 0xbfb8aa3b, v44
	v_mul_f32_e32 v143, 0xbfb8aa3b, v45
	v_mul_f32_e32 v144, 0xbfb8aa3b, v20
	v_mul_f32_e32 v145, 0xbfb8aa3b, v21
	v_mul_f32_e32 v146, 0xbfb8aa3b, v22
	v_mul_f32_e32 v147, 0xbfb8aa3b, v23
	v_mul_f32_e32 v148, 0xbfb8aa3b, v0
	v_mul_f32_e32 v149, 0xbfb8aa3b, v1
	v_mul_f32_e32 v150, 0xbfb8aa3b, v2
	v_mul_f32_e32 v151, 0xbfb8aa3b, v3
	v_exp_f32_e32 v136, v136
	v_exp_f32_e32 v137, v137
	v_exp_f32_e32 v138, v138
	v_exp_f32_e32 v139, v139
	v_exp_f32_e32 v140, v140
	v_exp_f32_e32 v141, v141
	v_exp_f32_e32 v142, v142
	v_exp_f32_e32 v143, v143
	v_exp_f32_e32 v144, v144
	v_exp_f32_e32 v145, v145
	v_exp_f32_e32 v146, v146
	v_exp_f32_e32 v147, v147
	v_exp_f32_e32 v148, v148
	v_exp_f32_e32 v149, v149
	v_exp_f32_e32 v150, v150
	v_exp_f32_e32 v151, v151
	v_add_f32_e32 v136, 1.0, v136
	v_add_f32_e32 v137, 1.0, v137
	v_add_f32_e32 v138, 1.0, v138
	v_add_f32_e32 v139, 1.0, v139
	v_add_f32_e32 v140, 1.0, v140
	v_add_f32_e32 v141, 1.0, v141
	v_add_f32_e32 v142, 1.0, v142
	v_add_f32_e32 v143, 1.0, v143
	v_add_f32_e32 v144, 1.0, v144
	v_add_f32_e32 v145, 1.0, v145
	v_add_f32_e32 v146, 1.0, v146
	v_add_f32_e32 v147, 1.0, v147
	v_add_f32_e32 v148, 1.0, v148
	v_add_f32_e32 v149, 1.0, v149
	v_add_f32_e32 v150, 1.0, v150
	v_add_f32_e32 v151, 1.0, v151
	v_rcp_f32_e32 v136, v136
	v_rcp_f32_e32 v137, v137
	v_rcp_f32_e32 v138, v138
	v_rcp_f32_e32 v139, v139
	v_rcp_f32_e32 v140, v140
	v_rcp_f32_e32 v141, v141
	v_rcp_f32_e32 v142, v142
	v_rcp_f32_e32 v143, v143
	v_rcp_f32_e32 v144, v144
	v_rcp_f32_e32 v145, v145
	v_rcp_f32_e32 v146, v146
	v_rcp_f32_e32 v147, v147
	v_rcp_f32_e32 v148, v148
	v_rcp_f32_e32 v149, v149
	v_rcp_f32_e32 v150, v150
	v_rcp_f32_e32 v151, v151
	v_mul_f32_e32 v58, v58, v136
	v_mul_f32_e32 v59, v59, v137
	v_mul_f32_e32 v60, v60, v138
	v_mul_f32_e32 v61, v61, v139
	v_mul_f32_e32 v42, v42, v140
	v_mul_f32_e32 v43, v43, v141
	v_mul_f32_e32 v44, v44, v142
	v_mul_f32_e32 v45, v45, v143
	v_mul_f32_e32 v20, v20, v144
	v_mul_f32_e32 v21, v21, v145
	v_mul_f32_e32 v22, v22, v146
	v_mul_f32_e32 v23, v23, v147
	v_mul_f32_e32 v0, v0, v148
	v_mul_f32_e32 v1, v1, v149
	v_mul_f32_e32 v2, v2, v150
	v_mul_f32_e32 v3, v3, v151
	v_mul_f32_e32 v58, s35, v58
	v_mul_f32_e32 v59, s35, v59
	v_mul_f32_e32 v60, s35, v60
	v_mul_f32_e32 v61, s35, v61
	v_mul_f32_e32 v42, s35, v42
	v_mul_f32_e32 v43, s35, v43
	v_mul_f32_e32 v44, s35, v44
	v_mul_f32_e32 v45, s35, v45
	v_mul_f32_e32 v20, s35, v20
	v_mul_f32_e32 v21, s35, v21
	v_mul_f32_e32 v22, s35, v22
	v_mul_f32_e32 v23, s35, v23
	v_mul_f32_e32 v0, s35, v0
	v_mul_f32_e32 v1, s35, v1
	v_mul_f32_e32 v2, s35, v2
	v_mul_f32_e32 v3, s35, v3
	v_cvt_pk_bf16_f32 v160, v58, v59
	v_cvt_pk_bf16_f32 v161, v60, v61
	v_cvt_pk_bf16_f32 v162, v42, v43
	v_cvt_pk_bf16_f32 v163, v44, v45
	v_cvt_pk_bf16_f32 v164, v20, v21
	v_cvt_pk_bf16_f32 v165, v22, v23
	v_cvt_pk_bf16_f32 v166, v0, v1
	v_cvt_pk_bf16_f32 v167, v2, v3
	ds_write_b64 v213, v[160:161]
	ds_write_b64 v213, v[162:163] offset:32
	ds_write_b64 v213, v[164:165] offset:64
	ds_write_b64 v213, v[166:167] offset:96
	ds_read2_b64 v[168:171], v214 offset1:1
	ds_read2_b64 v[172:175], v214 offset0:136 offset1:137
	v_add_u32_e32 v217, 0x108000, v215
	v_add_u32_e32 v218, 0x108000, v216
	s_waitcnt lgkmcnt(0)
	global_store_dwordx4 v217, v[168:171], s[16:17]
	global_store_dwordx4 v218, v[172:175], s[16:17]
	s_branch .LBB0_349
; DI unsigned pk_bf16(float a, float b) { f32x2_t v = {a, b}; bf16x2_t r = __builtin_convertvector(v, bf16x2_t); return __builtin_bit_cast(unsigned, r); }
; template <int EPI>
; DI void gemm_phase(const bf16_t* __restrict__ A, const bf16_t* __restrict__ Bt, const int K, const int N, const Params& p, const int layer_j, char* lds) {
;     ...
;             if (region == 2) {
;                 const int vc0 = col0 - 2048;
;                 const int b = row0 >> 11, t0 = row0 & 2047;
;                 bf16_t* dst = IT + ((size_t)(b * 1024 + vc0 + fr)) * SEQ + t0;
; #pragma unroll
;                 for (int bj = 0; bj < 2; ++bj)
; #pragma unroll
;                     for (int n = 0; n < 2; ++n)
; #pragma unroll
;                         for (int ai = 0; ai < 2; ++ai)
; #pragma unroll
;                             for (int m = 0; m < 4; ++m) { u32x2 o; o[0] = pk_bf16(acc[ai][bj][m][n][0], acc[ai][bj][m][n][1]); o[1] = pk_bf16(acc[ai][bj][m][n][2], acc[ai][bj][m][n][3]);
;                                 *(u32x2*)(dst + (size_t)(bj * 32 + n * 16) * SEQ + ai * 128 + m * 16) = o; }
.Lrec_epi_tr:
	v_mbcnt_lo_u32_b32 v212, -1, 0
	v_mbcnt_hi_u32_b32 v212, -1, v212
	s_mul_i32 s16, s71, 34
	s_add_i32 s16, s16, 0x20100
	v_and_b32_e32 v213, 15, v212
	v_lshrrev_b32_e32 v214, 4, v212
	v_mul_u32_u24_e32 v213, 136, v213
	v_lshl_add_u32 v213, v214, 3, v213
	v_add_u32_e32 v213, s16, v213
	v_lshrrev_b32_e32 v215, 3, v212
	v_and_b32_e32 v216, 7, v212
	v_mul_u32_u24_e32 v214, 136, v215
	v_lshl_add_u32 v214, v216, 4, v214
	v_add_u32_e32 v214, s16, v214
	v_readlane_b32 s16, v254, 14
	v_readlane_b32 s17, v254, 7
	v_lshlrev_b32_e32 v216, 4, v216
	v_add_u32_e32 v215, s16, v215
	s_lshl_b32 s17, s17, 1
	s_mov_b32 s16, 4096
	v_mad_u32_u24 v215, v215, s16, v216
	v_add_u32_e32 v215, s17, v215
	v_add_u32_e32 v216, 0x8000, v215
	v_readlane_b32 s28, v255, 8
	v_readlane_b32 s29, v255, 9
	s_lshr_b32 s16, s8, 3
	s_lshl_b32 s16, s16, 10
	s_lshl_b32 s17, s4, 8
	s_add_i32 s16, s16, s17
	s_sub_u32 s16, s16, 0x800
	s_lshl_b32 s16, s16, 12
	s_and_b32 s17, s8, 7
	s_lshl_b32 s17, s17, 9
	s_add_u32 s16, s16, s17
	s_add_u32 s16, s16, s28
	s_addc_u32 s17, s29, 0
	v_cvt_pk_bf16_f32 v160, v126, v127
	v_cvt_pk_bf16_f32 v161, v128, v129
	v_cvt_pk_bf16_f32 v162, v110, v111
	v_cvt_pk_bf16_f32 v163, v112, v113
	v_cvt_pk_bf16_f32 v164, v94, v95
	v_cvt_pk_bf16_f32 v165, v96, v97
	v_cvt_pk_bf16_f32 v166, v78, v79
	v_cvt_pk_bf16_f32 v167, v80, v81
	ds_write_b64 v213, v[160:161]
	ds_write_b64 v213, v[162:163] offset:32
	ds_write_b64 v213, v[164:165] offset:64
	ds_write_b64 v213, v[166:167] offset:96
	ds_read2_b64 v[168:171], v214 offset1:1
	ds_read2_b64 v[172:175], v214 offset0:136 offset1:137
	s_waitcnt lgkmcnt(0)
	global_store_dwordx4 v215, v[168:171], s[16:17]
	global_store_dwordx4 v216, v[172:175], s[16:17]
	v_cvt_pk_bf16_f32 v160, v70, v71
	v_cvt_pk_bf16_f32 v161, v72, v73
	v_cvt_pk_bf16_f32 v162, v66, v67
	v_cvt_pk_bf16_f32 v163, v68, v69
	v_cvt_pk_bf16_f32 v164, v62, v63
	v_cvt_pk_bf16_f32 v165, v64, v65
	v_cvt_pk_bf16_f32 v166, v58, v59
	v_cvt_pk_bf16_f32 v167, v60, v61
	ds_write_b64 v213, v[160:161]
	ds_write_b64 v213, v[162:163] offset:32
	ds_write_b64 v213, v[164:165] offset:64
	ds_write_b64 v213, v[166:167] offset:96
	ds_read2_b64 v[168:171], v214 offset1:1
	ds_read2_b64 v[172:175], v214 offset0:136 offset1:137
	v_add_u32_e32 v217, 0x100, v215
	v_add_u32_e32 v218, 0x100, v216
	s_waitcnt lgkmcnt(0)
	global_store_dwordx4 v217, v[168:171], s[16:17]
	global_store_dwordx4 v218, v[172:175], s[16:17]
	v_cvt_pk_bf16_f32 v160, v122, v123
	v_cvt_pk_bf16_f32 v161, v124, v125
	v_cvt_pk_bf16_f32 v162, v106, v107
	v_cvt_pk_bf16_f32 v163, v108, v109
	v_cvt_pk_bf16_f32 v164, v90, v91
	v_cvt_pk_bf16_f32 v165, v92, v93
	v_cvt_pk_bf16_f32 v166, v74, v75
	v_cvt_pk_bf16_f32 v167, v76, v77
	ds_write_b64 v213, v[160:161]
	ds_write_b64 v213, v[162:163] offset:32
	ds_write_b64 v213, v[164:165] offset:64
	ds_write_b64 v213, v[166:167] offset:96
	ds_read2_b64 v[168:171], v214 offset1:1
	ds_read2_b64 v[172:175], v214 offset0:136 offset1:137
	v_add_u32_e32 v217, 0x10000, v215
	v_add_u32_e32 v218, 0x10000, v216
	s_waitcnt lgkmcnt(0)
	global_store_dwordx4 v217, v[168:171], s[16:17]
	global_store_dwordx4 v218, v[172:175], s[16:17]
	v_cvt_pk_bf16_f32 v160, v54, v55
	v_cvt_pk_bf16_f32 v161, v56, v57
	v_cvt_pk_bf16_f32 v162, v50, v51
	v_cvt_pk_bf16_f32 v163, v52, v53
	v_cvt_pk_bf16_f32 v164, v46, v47
	v_cvt_pk_bf16_f32 v165, v48, v49
	v_cvt_pk_bf16_f32 v166, v42, v43
	v_cvt_pk_bf16_f32 v167, v44, v45
	ds_write_b64 v213, v[160:161]
	ds_write_b64 v213, v[162:163] offset:32
	ds_write_b64 v213, v[164:165] offset:64
	ds_write_b64 v213, v[166:167] offset:96
	ds_read2_b64 v[168:171], v214 offset1:1
	ds_read2_b64 v[172:175], v214 offset0:136 offset1:137
	v_add_u32_e32 v217, 0x10100, v215
	v_add_u32_e32 v218, 0x10100, v216
	s_waitcnt lgkmcnt(0)
	global_store_dwordx4 v217, v[168:171], s[16:17]
	global_store_dwordx4 v218, v[172:175], s[16:17]
	v_cvt_pk_bf16_f32 v160, v118, v119
	v_cvt_pk_bf16_f32 v161, v120, v121
	v_cvt_pk_bf16_f32 v162, v102, v103
	v_cvt_pk_bf16_f32 v163, v104, v105
	v_cvt_pk_bf16_f32 v164, v86, v87
	v_cvt_pk_bf16_f32 v165, v88, v89
	v_cvt_pk_bf16_f32 v166, v38, v39
	v_cvt_pk_bf16_f32 v167, v40, v41
	ds_write_b64 v213, v[160:161]
	ds_write_b64 v213, v[162:163] offset:32
	ds_write_b64 v213, v[164:165] offset:64
	ds_write_b64 v213, v[166:167] offset:96
	ds_read2_b64 v[168:171], v214 offset1:1
	ds_read2_b64 v[172:175], v214 offset0:136 offset1:137
	v_add_u32_e32 v217, 0x20000, v215
	v_add_u32_e32 v218, 0x20000, v216
	s_waitcnt lgkmcnt(0)
	global_store_dwordx4 v217, v[168:171], s[16:17]
	global_store_dwordx4 v218, v[172:175], s[16:17]
	v_cvt_pk_bf16_f32 v160, v34, v35
	v_cvt_pk_bf16_f32 v161, v36, v37
	v_cvt_pk_bf16_f32 v162, v28, v29
	v_cvt_pk_bf16_f32 v163, v30, v31
	v_cvt_pk_bf16_f32 v164, v24, v25
	v_cvt_pk_bf16_f32 v165, v26, v27
	v_cvt_pk_bf16_f32 v166, v20, v21
	v_cvt_pk_bf16_f32 v167, v22, v23
	ds_write_b64 v213, v[160:161]
	ds_write_b64 v213, v[162:163] offset:32
	ds_write_b64 v213, v[164:165] offset:64
	ds_write_b64 v213, v[166:167] offset:96
	ds_read2_b64 v[168:171], v214 offset1:1
	ds_read2_b64 v[172:175], v214 offset0:136 offset1:137
	v_add_u32_e32 v217, 0x20100, v215
	v_add_u32_e32 v218, 0x20100, v216
	s_waitcnt lgkmcnt(0)
	global_store_dwordx4 v217, v[168:171], s[16:17]
	global_store_dwordx4 v218, v[172:175], s[16:17]
	v_cvt_pk_bf16_f32 v160, v114, v115
	v_cvt_pk_bf16_f32 v161, v116, v117
	v_cvt_pk_bf16_f32 v162, v98, v99
	v_cvt_pk_bf16_f32 v163, v100, v101
	v_cvt_pk_bf16_f32 v164, v82, v83
	v_cvt_pk_bf16_f32 v165, v84, v85
	v_cvt_pk_bf16_f32 v166, v16, v17
	v_cvt_pk_bf16_f32 v167, v18, v19
	ds_write_b64 v213, v[160:161]
	ds_write_b64 v213, v[162:163] offset:32
	ds_write_b64 v213, v[164:165] offset:64
	ds_write_b64 v213, v[166:167] offset:96
	ds_read2_b64 v[168:171], v214 offset1:1
	ds_read2_b64 v[172:175], v214 offset0:136 offset1:137
	v_add_u32_e32 v217, 0x30000, v215
	v_add_u32_e32 v218, 0x30000, v216
	s_waitcnt lgkmcnt(0)
	global_store_dwordx4 v217, v[168:171], s[16:17]
	global_store_dwordx4 v218, v[172:175], s[16:17]
	v_cvt_pk_bf16_f32 v160, v12, v13
	v_cvt_pk_bf16_f32 v161, v14, v15
	v_cvt_pk_bf16_f32 v162, v8, v9
	v_cvt_pk_bf16_f32 v163, v10, v11
	v_cvt_pk_bf16_f32 v164, v4, v5
	v_cvt_pk_bf16_f32 v165, v6, v7
	v_cvt_pk_bf16_f32 v166, v0, v1
	v_cvt_pk_bf16_f32 v167, v2, v3
	ds_write_b64 v213, v[160:161]
	ds_write_b64 v213, v[162:163] offset:32
	ds_write_b64 v213, v[164:165] offset:64
	ds_write_b64 v213, v[166:167] offset:96
	ds_read2_b64 v[168:171], v214 offset1:1
	ds_read2_b64 v[172:175], v214 offset0:136 offset1:137
	v_add_u32_e32 v217, 0x30100, v215
	v_add_u32_e32 v218, 0x30100, v216
	s_waitcnt lgkmcnt(0)
	global_store_dwordx4 v217, v[168:171], s[16:17]
	global_store_dwordx4 v218, v[172:175], s[16:17]
	s_branch .LBB0_349
